# last-layer resid passes no longer store the bf16 residual stream / next-layer rstd (no reader after the final pass): 64 MB less write traffic
# speedup vs baseline: 1.0041x; 1.0041x over previous
; __device__ __forceinline__ float bflo(unsigned w) { return __uint_as_float(w << 16); }
; __device__ __forceinline__ float bfhi(unsigned w) { return __uint_as_float(w & 0xffff0000u); }
; __device__ __forceinline__ void resid_rows(bf16_t* R, const bf16_t* Y, const float* ssqY, const float* g, float* rstd_out, float* outf, bool wf32, int row_lo, int row_hi, int yoff, int gw, int NGW, int lane) {
;     ...
;     for (int row0 = row_lo + gw; row0 < row_hi; row0 += RP * NGW) {
;         u32x4 rr[RP][2], oo[RP][2]; float ssv[RP];
; #pragma unroll
;         for (int k = 0; k < RP; ++k) { const int row = row0 + k * NGW; const bool ok = row < row_hi; const int rw = ok ? row : row0;
;             ssv[k] = ssqY[rw];
; #pragma unroll
;             for (int j = 0; j < 2; ++j) { const int c = 8 * lane + 512 * j; rr[k][j] = *(const u32x4*)(R + (size_t)rw * DM + c); oo[k][j] = *(const u32x4*)(Y + (size_t)(rw - yoff) * DM + c); } }
; #pragma unroll
;         for (int k = 0; k < RP; ++k) { const int row = row0 + k * NGW; if (row < row_hi) {
;             const float rs = __builtin_amdgcn_rsqf(ssv[k] * (1.0f / DM) + RMS_EPS); float s = 0.f;
; #pragma unroll
;             for (int j = 0; j < 2; ++j) { const int c = 8 * lane + 512 * j; const u32x4 r = rr[k][j], o = oo[k][j]; const f32x4 ga = gv[j][0], gb = gv[j][1];
;                 f32x4 ya, yb; ya[0] = bflo(r.x) + bflo(o.x) * rs * ga[0]; ya[1] = bfhi(r.x) + bfhi(o.x) * rs * ga[1]; ya[2] = bflo(r.y) + bflo(o.y) * rs * ga[2]; ya[3] = bfhi(r.y) + bfhi(o.y) * rs * ga[3];
;                 yb[0] = bflo(r.z) + bflo(o.z) * rs * gb[0]; yb[1] = bfhi(r.z) + bfhi(o.z) * rs * gb[1]; yb[2] = bflo(r.w) + bflo(o.w) * rs * gb[2]; yb[3] = bfhi(r.w) + bfhi(o.w) * rs * gb[3];
;                 if (wf32) { *(f32x4*)(outf + (size_t)row * DM + c) = ya; *(f32x4*)(outf + (size_t)row * DM + c + 4) = yb; }
;                 s += (ya[0] * ya[0] + ya[1] * ya[1]) + (ya[2] * ya[2] + ya[3] * ya[3]) + (yb[0] * yb[0] + yb[1] * yb[1]) + (yb[2] * yb[2] + yb[3] * yb[3]);
;                 u32x4 w; w.x = pk2(ya[0], ya[1]); w.y = pk2(ya[2], ya[3]); w.z = pk2(yb[0], yb[1]); w.w = pk2(yb[2], yb[3]); *(u32x4*)(R + (size_t)row * DM + c) = w; }
;             s = wave_sum(s); if (lane == 0) rstd_out[row] = __builtin_amdgcn_rsqf(s * (1.0f / DM) + RMS_EPS); } }
.Lrs2_last1:
	v_lshrrev_b32_e32 v114, 6, v0
	v_readlane_b32 s12, v255, 49
	v_readlane_b32 s13, v255, 4
	v_readfirstlane_b32 s18, v114
	s_load_dwordx2 s[4:5], s[0:1], 0x98
	s_load_dwordx2 s[10:11], s[0:1], 0x68
	s_load_dwordx2 s[6:7], s[0:1], 0x90
	s_add_i32 s13, s13, s18
	v_and_b32_e32 v115, 63, v0
	v_lshlrev_b32_e32 v114, 4, v115
	v_lshlrev_b32_e32 v115, 5, v115
	s_lshl_b32 s18, s12, 12
	s_lshl_b32 s19, s12, 18
	s_bfm_b64 s[8:9], 1, 63
	s_waitcnt lgkmcnt(0)
	s_add_u32 s10, s10, s18
	s_addc_u32 s11, s11, 0
	global_load_dwordx4 v[2:5], v115, s[10:11] offset:2048
	global_load_dwordx4 v[6:9], v115, s[10:11] offset:2064
	global_load_dwordx4 v[10:13], v115, s[10:11]
	global_load_dwordx4 v[14:17], v115, s[10:11] offset:16
	s_lshl_b32 s18, s13, 11
	v_add_u32_e32 v18, s18, v114
	v_mov_b32_e32 v19, v18
	v_mov_b32_e32 v20, v18
	s_lshl_b32 s18, s13, 2
	v_mov_b32_e32 v22, s18
	s_add_i32 s18, s18, s19
	v_mov_b32_e32 v21, s18
	s_lshl_b32 s18, s13, 12
	v_add_u32_e32 v23, s18, v115
	v_add_u32_e32 v18, 0x5001000, v18
	v_add_u32_e32 v21, 0x2d70000, v21
	global_load_dwordx4 v[24:27], v18, s[4:5]
	global_load_dwordx4 v[32:35], v20, s[6:7]
	global_load_dwordx4 v[28:31], v18, s[4:5] offset:1024
	global_load_dwordx4 v[36:39], v20, s[6:7] offset:1024
	global_load_dword v40, v21, s[4:5]
	v_add_u32_e32 v18, 0x400000, v18
	v_add_u32_e32 v20, 0x400000, v20
	v_add_u32_e32 v21, 0x2000, v21
	global_load_dwordx4 v[42:45], v18, s[4:5]
	global_load_dwordx4 v[50:53], v20, s[6:7]
	global_load_dwordx4 v[46:49], v18, s[4:5] offset:1024
	global_load_dwordx4 v[54:57], v20, s[6:7] offset:1024
	global_load_dword v58, v21, s[4:5]
	v_add_u32_e32 v18, 0x400000, v18
	v_add_u32_e32 v20, 0x400000, v20
	v_add_u32_e32 v21, 0x2000, v21
	global_load_dwordx4 v[60:63], v18, s[4:5]
	global_load_dwordx4 v[68:71], v20, s[6:7]
	global_load_dwordx4 v[64:67], v18, s[4:5] offset:1024
	global_load_dwordx4 v[72:75], v20, s[6:7] offset:1024
	global_load_dword v76, v21, s[4:5]
	v_add_u32_e32 v18, 0x400000, v18
	v_add_u32_e32 v20, 0x400000, v20
	v_add_u32_e32 v21, 0x2000, v21
	global_load_dwordx4 v[78:81], v18, s[4:5]
	global_load_dwordx4 v[86:89], v20, s[6:7]
	global_load_dwordx4 v[82:85], v18, s[4:5] offset:1024
	global_load_dwordx4 v[90:93], v20, s[6:7] offset:1024
	global_load_dword v94, v21, s[4:5]
	s_waitcnt vmcnt(15)
	v_fmamk_f32 v96, v40, 0x3a800000, v244
	v_rsq_f32_e32 v96, v96
	v_add_u32_e32 v19, 0x5001000, v19
	v_add_u32_e32 v23, 0x4000000, v23
	v_lshlrev_b32_e32 v106, 16, v32
	v_and_b32_e32 v107, 0xffff0000, v32
	v_lshlrev_b32_e32 v108, 16, v24
	v_and_b32_e32 v109, 0xffff0000, v24
	v_pk_mul_f32 v[106:107], v[96:97], v[106:107] op_sel_hi:[0,1]
	v_pk_fma_f32 v[98:99], v[10:11], v[106:107], v[108:109]
	v_lshlrev_b32_e32 v106, 16, v33
	v_and_b32_e32 v107, 0xffff0000, v33
	v_lshlrev_b32_e32 v108, 16, v25
	v_and_b32_e32 v109, 0xffff0000, v25
	v_pk_mul_f32 v[106:107], v[96:97], v[106:107] op_sel_hi:[0,1]
	v_pk_fma_f32 v[100:101], v[12:13], v[106:107], v[108:109]
	v_lshlrev_b32_e32 v106, 16, v34
	v_and_b32_e32 v107, 0xffff0000, v34
	v_lshlrev_b32_e32 v108, 16, v26
	v_and_b32_e32 v109, 0xffff0000, v26
	v_pk_mul_f32 v[106:107], v[96:97], v[106:107] op_sel_hi:[0,1]
	v_pk_fma_f32 v[102:103], v[14:15], v[106:107], v[108:109]
	v_lshlrev_b32_e32 v106, 16, v35
	v_and_b32_e32 v107, 0xffff0000, v35
	v_lshlrev_b32_e32 v108, 16, v27
	v_and_b32_e32 v109, 0xffff0000, v27
	v_pk_mul_f32 v[106:107], v[96:97], v[106:107] op_sel_hi:[0,1]
	v_pk_fma_f32 v[104:105], v[16:17], v[106:107], v[108:109]
	global_store_dwordx4 v23, v[98:101], s[6:7]
	global_store_dwordx4 v23, v[102:105], s[6:7] offset:16
	v_lshlrev_b32_e32 v106, 16, v36
	v_and_b32_e32 v107, 0xffff0000, v36
	v_lshlrev_b32_e32 v108, 16, v28
	v_and_b32_e32 v109, 0xffff0000, v28
	v_pk_mul_f32 v[106:107], v[96:97], v[106:107] op_sel_hi:[0,1]
	v_pk_fma_f32 v[98:99], v[2:3], v[106:107], v[108:109]
	v_lshlrev_b32_e32 v106, 16, v37
	v_and_b32_e32 v107, 0xffff0000, v37
	v_lshlrev_b32_e32 v108, 16, v29
	v_and_b32_e32 v109, 0xffff0000, v29
	v_pk_mul_f32 v[106:107], v[96:97], v[106:107] op_sel_hi:[0,1]
	v_pk_fma_f32 v[100:101], v[4:5], v[106:107], v[108:109]
	v_lshlrev_b32_e32 v106, 16, v38
	v_and_b32_e32 v107, 0xffff0000, v38
	v_lshlrev_b32_e32 v108, 16, v30
	v_and_b32_e32 v109, 0xffff0000, v30
	v_pk_mul_f32 v[106:107], v[96:97], v[106:107] op_sel_hi:[0,1]
	v_pk_fma_f32 v[102:103], v[6:7], v[106:107], v[108:109]
	v_lshlrev_b32_e32 v106, 16, v39
	v_and_b32_e32 v107, 0xffff0000, v39
	v_lshlrev_b32_e32 v108, 16, v31
	v_and_b32_e32 v109, 0xffff0000, v31
	v_pk_mul_f32 v[106:107], v[96:97], v[106:107] op_sel_hi:[0,1]
	v_pk_fma_f32 v[104:105], v[8:9], v[106:107], v[108:109]
	global_store_dwordx4 v23, v[98:101], s[6:7] offset:2048
	global_store_dwordx4 v23, v[102:105], s[6:7] offset:2064
	v_add_u32_e32 v18, 0x400000, v18
	v_add_u32_e32 v20, 0x400000, v20
	v_add_u32_e32 v21, 0x2000, v21
	global_load_dwordx4 v[24:27], v18, s[4:5]
	global_load_dwordx4 v[32:35], v20, s[6:7]
	global_load_dwordx4 v[28:31], v18, s[4:5] offset:1024
	global_load_dwordx4 v[36:39], v20, s[6:7] offset:1024
	global_load_dword v40, v21, s[4:5]
	s_waitcnt vmcnt(19)
; __device__ __forceinline__ float bflo(unsigned w) { return __uint_as_float(w << 16); }
; __device__ __forceinline__ float bfhi(unsigned w) { return __uint_as_float(w & 0xffff0000u); }
; __device__ __forceinline__ void resid_rows(bf16_t* R, const bf16_t* Y, const float* ssqY, const float* g, float* rstd_out, float* outf, bool wf32, int row_lo, int row_hi, int yoff, int gw, int NGW, int lane) {
;     ...
;     for (int row0 = row_lo + gw; row0 < row_hi; row0 += RP * NGW) {
;         u32x4 rr[RP][2], oo[RP][2]; float ssv[RP];
; #pragma unroll
;         for (int k = 0; k < RP; ++k) { const int row = row0 + k * NGW; const bool ok = row < row_hi; const int rw = ok ? row : row0;
;             ssv[k] = ssqY[rw];
; #pragma unroll
;             for (int j = 0; j < 2; ++j) { const int c = 8 * lane + 512 * j; rr[k][j] = *(const u32x4*)(R + (size_t)rw * DM + c); oo[k][j] = *(const u32x4*)(Y + (size_t)(rw - yoff) * DM + c); } }
; #pragma unroll
;         for (int k = 0; k < RP; ++k) { const int row = row0 + k * NGW; if (row < row_hi) {
;             const float rs = __builtin_amdgcn_rsqf(ssv[k] * (1.0f / DM) + RMS_EPS); float s = 0.f;
; #pragma unroll
;             for (int j = 0; j < 2; ++j) { const int c = 8 * lane + 512 * j; const u32x4 r = rr[k][j], o = oo[k][j]; const f32x4 ga = gv[j][0], gb = gv[j][1];
;                 f32x4 ya, yb; ya[0] = bflo(r.x) + bflo(o.x) * rs * ga[0]; ya[1] = bfhi(r.x) + bfhi(o.x) * rs * ga[1]; ya[2] = bflo(r.y) + bflo(o.y) * rs * ga[2]; ya[3] = bfhi(r.y) + bfhi(o.y) * rs * ga[3];
;                 yb[0] = bflo(r.z) + bflo(o.z) * rs * gb[0]; yb[1] = bfhi(r.z) + bfhi(o.z) * rs * gb[1]; yb[2] = bflo(r.w) + bflo(o.w) * rs * gb[2]; yb[3] = bfhi(r.w) + bfhi(o.w) * rs * gb[3];
;                 if (wf32) { *(f32x4*)(outf + (size_t)row * DM + c) = ya; *(f32x4*)(outf + (size_t)row * DM + c + 4) = yb; }
;                 s += (ya[0] * ya[0] + ya[1] * ya[1]) + (ya[2] * ya[2] + ya[3] * ya[3]) + (yb[0] * yb[0] + yb[1] * yb[1]) + (yb[2] * yb[2] + yb[3] * yb[3]);
;                 u32x4 w; w.x = pk2(ya[0], ya[1]); w.y = pk2(ya[2], ya[3]); w.z = pk2(yb[0], yb[1]); w.w = pk2(yb[2], yb[3]); *(u32x4*)(R + (size_t)row * DM + c) = w; }
;             s = wave_sum(s); if (lane == 0) rstd_out[row] = __builtin_amdgcn_rsqf(s * (1.0f / DM) + RMS_EPS); } }
	v_fmamk_f32 v96, v58, 0x3a800000, v244
	v_rsq_f32_e32 v96, v96
	v_add_u32_e32 v19, 0x400000, v19
	v_add_u32_e32 v23, 0x800000, v23
	v_lshlrev_b32_e32 v106, 16, v50
	v_and_b32_e32 v107, 0xffff0000, v50
	v_lshlrev_b32_e32 v108, 16, v42
	v_and_b32_e32 v109, 0xffff0000, v42
	v_pk_mul_f32 v[106:107], v[96:97], v[106:107] op_sel_hi:[0,1]
	v_pk_fma_f32 v[98:99], v[10:11], v[106:107], v[108:109]
	v_lshlrev_b32_e32 v106, 16, v51
	v_and_b32_e32 v107, 0xffff0000, v51
	v_lshlrev_b32_e32 v108, 16, v43
	v_and_b32_e32 v109, 0xffff0000, v43
	v_pk_mul_f32 v[106:107], v[96:97], v[106:107] op_sel_hi:[0,1]
	v_pk_fma_f32 v[100:101], v[12:13], v[106:107], v[108:109]
	v_lshlrev_b32_e32 v106, 16, v52
	v_and_b32_e32 v107, 0xffff0000, v52
	v_lshlrev_b32_e32 v108, 16, v44
	v_and_b32_e32 v109, 0xffff0000, v44
	v_pk_mul_f32 v[106:107], v[96:97], v[106:107] op_sel_hi:[0,1]
	v_pk_fma_f32 v[102:103], v[14:15], v[106:107], v[108:109]
	v_lshlrev_b32_e32 v106, 16, v53
	v_and_b32_e32 v107, 0xffff0000, v53
	v_lshlrev_b32_e32 v108, 16, v45
	v_and_b32_e32 v109, 0xffff0000, v45
	v_pk_mul_f32 v[106:107], v[96:97], v[106:107] op_sel_hi:[0,1]
	v_pk_fma_f32 v[104:105], v[16:17], v[106:107], v[108:109]
	global_store_dwordx4 v23, v[98:101], s[6:7]
	global_store_dwordx4 v23, v[102:105], s[6:7] offset:16
	v_lshlrev_b32_e32 v106, 16, v54
	v_and_b32_e32 v107, 0xffff0000, v54
	v_lshlrev_b32_e32 v108, 16, v46
	v_and_b32_e32 v109, 0xffff0000, v46
	v_pk_mul_f32 v[106:107], v[96:97], v[106:107] op_sel_hi:[0,1]
	v_pk_fma_f32 v[98:99], v[2:3], v[106:107], v[108:109]
	v_lshlrev_b32_e32 v106, 16, v55
	v_and_b32_e32 v107, 0xffff0000, v55
	v_lshlrev_b32_e32 v108, 16, v47
	v_and_b32_e32 v109, 0xffff0000, v47
	v_pk_mul_f32 v[106:107], v[96:97], v[106:107] op_sel_hi:[0,1]
	v_pk_fma_f32 v[100:101], v[4:5], v[106:107], v[108:109]
	v_lshlrev_b32_e32 v106, 16, v56
	v_and_b32_e32 v107, 0xffff0000, v56
	v_lshlrev_b32_e32 v108, 16, v48
	v_and_b32_e32 v109, 0xffff0000, v48
	v_pk_mul_f32 v[106:107], v[96:97], v[106:107] op_sel_hi:[0,1]
	v_pk_fma_f32 v[102:103], v[6:7], v[106:107], v[108:109]
	v_lshlrev_b32_e32 v106, 16, v57
	v_and_b32_e32 v107, 0xffff0000, v57
	v_lshlrev_b32_e32 v108, 16, v49
	v_and_b32_e32 v109, 0xffff0000, v49
	v_pk_mul_f32 v[106:107], v[96:97], v[106:107] op_sel_hi:[0,1]
	v_pk_fma_f32 v[104:105], v[8:9], v[106:107], v[108:109]
	global_store_dwordx4 v23, v[98:101], s[6:7] offset:2048
	global_store_dwordx4 v23, v[102:105], s[6:7] offset:2064
	v_add_u32_e32 v18, 0x400000, v18
	v_add_u32_e32 v20, 0x400000, v20
	v_add_u32_e32 v21, 0x2000, v21
	global_load_dwordx4 v[42:45], v18, s[4:5]
	global_load_dwordx4 v[50:53], v20, s[6:7]
	global_load_dwordx4 v[46:49], v18, s[4:5] offset:1024
	global_load_dwordx4 v[54:57], v20, s[6:7] offset:1024
	global_load_dword v58, v21, s[4:5]
	s_waitcnt vmcnt(23)
	v_fmamk_f32 v96, v76, 0x3a800000, v244
	v_rsq_f32_e32 v96, v96
	v_add_u32_e32 v19, 0x400000, v19
	v_add_u32_e32 v23, 0x800000, v23
	v_lshlrev_b32_e32 v106, 16, v68
	v_and_b32_e32 v107, 0xffff0000, v68
	v_lshlrev_b32_e32 v108, 16, v60
	v_and_b32_e32 v109, 0xffff0000, v60
	v_pk_mul_f32 v[106:107], v[96:97], v[106:107] op_sel_hi:[0,1]
	v_pk_fma_f32 v[98:99], v[10:11], v[106:107], v[108:109]
	v_lshlrev_b32_e32 v106, 16, v69
	v_and_b32_e32 v107, 0xffff0000, v69
	v_lshlrev_b32_e32 v108, 16, v61
	v_and_b32_e32 v109, 0xffff0000, v61
	v_pk_mul_f32 v[106:107], v[96:97], v[106:107] op_sel_hi:[0,1]
	v_pk_fma_f32 v[100:101], v[12:13], v[106:107], v[108:109]
	v_lshlrev_b32_e32 v106, 16, v70
	v_and_b32_e32 v107, 0xffff0000, v70
	v_lshlrev_b32_e32 v108, 16, v62
	v_and_b32_e32 v109, 0xffff0000, v62
	v_pk_mul_f32 v[106:107], v[96:97], v[106:107] op_sel_hi:[0,1]
	v_pk_fma_f32 v[102:103], v[14:15], v[106:107], v[108:109]
	v_lshlrev_b32_e32 v106, 16, v71
	v_and_b32_e32 v107, 0xffff0000, v71
	v_lshlrev_b32_e32 v108, 16, v63
	v_and_b32_e32 v109, 0xffff0000, v63
	v_pk_mul_f32 v[106:107], v[96:97], v[106:107] op_sel_hi:[0,1]
	v_pk_fma_f32 v[104:105], v[16:17], v[106:107], v[108:109]
	global_store_dwordx4 v23, v[98:101], s[6:7]
	global_store_dwordx4 v23, v[102:105], s[6:7] offset:16
	v_lshlrev_b32_e32 v106, 16, v72
	v_and_b32_e32 v107, 0xffff0000, v72
	v_lshlrev_b32_e32 v108, 16, v64
	v_and_b32_e32 v109, 0xffff0000, v64
	v_pk_mul_f32 v[106:107], v[96:97], v[106:107] op_sel_hi:[0,1]
	v_pk_fma_f32 v[98:99], v[2:3], v[106:107], v[108:109]
	v_lshlrev_b32_e32 v106, 16, v73
	v_and_b32_e32 v107, 0xffff0000, v73
	v_lshlrev_b32_e32 v108, 16, v65
	v_and_b32_e32 v109, 0xffff0000, v65
	v_pk_mul_f32 v[106:107], v[96:97], v[106:107] op_sel_hi:[0,1]
	v_pk_fma_f32 v[100:101], v[4:5], v[106:107], v[108:109]
	v_lshlrev_b32_e32 v106, 16, v74
	v_and_b32_e32 v107, 0xffff0000, v74
	v_lshlrev_b32_e32 v108, 16, v66
	v_and_b32_e32 v109, 0xffff0000, v66
	v_pk_mul_f32 v[106:107], v[96:97], v[106:107] op_sel_hi:[0,1]
	v_pk_fma_f32 v[102:103], v[6:7], v[106:107], v[108:109]
	v_lshlrev_b32_e32 v106, 16, v75
	v_and_b32_e32 v107, 0xffff0000, v75
	v_lshlrev_b32_e32 v108, 16, v67
	v_and_b32_e32 v109, 0xffff0000, v67
	v_pk_mul_f32 v[106:107], v[96:97], v[106:107] op_sel_hi:[0,1]
	v_pk_fma_f32 v[104:105], v[8:9], v[106:107], v[108:109]
	global_store_dwordx4 v23, v[98:101], s[6:7] offset:2048
	global_store_dwordx4 v23, v[102:105], s[6:7] offset:2064
	v_add_u32_e32 v18, 0x400000, v18
	v_add_u32_e32 v20, 0x400000, v20
	v_add_u32_e32 v21, 0x2000, v21
	global_load_dwordx4 v[60:63], v18, s[4:5]
	global_load_dwordx4 v[68:71], v20, s[6:7]
	global_load_dwordx4 v[64:67], v18, s[4:5] offset:1024
	global_load_dwordx4 v[72:75], v20, s[6:7] offset:1024
	global_load_dword v76, v21, s[4:5]
	s_waitcnt vmcnt(27)
; __device__ __forceinline__ float bflo(unsigned w) { return __uint_as_float(w << 16); }
; __device__ __forceinline__ float bfhi(unsigned w) { return __uint_as_float(w & 0xffff0000u); }
; __device__ __forceinline__ void resid_rows(bf16_t* R, const bf16_t* Y, const float* ssqY, const float* g, float* rstd_out, float* outf, bool wf32, int row_lo, int row_hi, int yoff, int gw, int NGW, int lane) {
;     ...
;     for (int row0 = row_lo + gw; row0 < row_hi; row0 += RP * NGW) {
;         u32x4 rr[RP][2], oo[RP][2]; float ssv[RP];
; #pragma unroll
;         for (int k = 0; k < RP; ++k) { const int row = row0 + k * NGW; const bool ok = row < row_hi; const int rw = ok ? row : row0;
;             ssv[k] = ssqY[rw];
; #pragma unroll
;             for (int j = 0; j < 2; ++j) { const int c = 8 * lane + 512 * j; rr[k][j] = *(const u32x4*)(R + (size_t)rw * DM + c); oo[k][j] = *(const u32x4*)(Y + (size_t)(rw - yoff) * DM + c); } }
; #pragma unroll
;         for (int k = 0; k < RP; ++k) { const int row = row0 + k * NGW; if (row < row_hi) {
;             const float rs = __builtin_amdgcn_rsqf(ssv[k] * (1.0f / DM) + RMS_EPS); float s = 0.f;
; #pragma unroll
;             for (int j = 0; j < 2; ++j) { const int c = 8 * lane + 512 * j; const u32x4 r = rr[k][j], o = oo[k][j]; const f32x4 ga = gv[j][0], gb = gv[j][1];
;                 f32x4 ya, yb; ya[0] = bflo(r.x) + bflo(o.x) * rs * ga[0]; ya[1] = bfhi(r.x) + bfhi(o.x) * rs * ga[1]; ya[2] = bflo(r.y) + bflo(o.y) * rs * ga[2]; ya[3] = bfhi(r.y) + bfhi(o.y) * rs * ga[3];
;                 yb[0] = bflo(r.z) + bflo(o.z) * rs * gb[0]; yb[1] = bfhi(r.z) + bfhi(o.z) * rs * gb[1]; yb[2] = bflo(r.w) + bflo(o.w) * rs * gb[2]; yb[3] = bfhi(r.w) + bfhi(o.w) * rs * gb[3];
;                 if (wf32) { *(f32x4*)(outf + (size_t)row * DM + c) = ya; *(f32x4*)(outf + (size_t)row * DM + c + 4) = yb; }
;                 s += (ya[0] * ya[0] + ya[1] * ya[1]) + (ya[2] * ya[2] + ya[3] * ya[3]) + (yb[0] * yb[0] + yb[1] * yb[1]) + (yb[2] * yb[2] + yb[3] * yb[3]);
;                 u32x4 w; w.x = pk2(ya[0], ya[1]); w.y = pk2(ya[2], ya[3]); w.z = pk2(yb[0], yb[1]); w.w = pk2(yb[2], yb[3]); *(u32x4*)(R + (size_t)row * DM + c) = w; }
;             s = wave_sum(s); if (lane == 0) rstd_out[row] = __builtin_amdgcn_rsqf(s * (1.0f / DM) + RMS_EPS); } }
	v_fmamk_f32 v96, v94, 0x3a800000, v244
	v_rsq_f32_e32 v96, v96
	v_add_u32_e32 v19, 0x400000, v19
	v_add_u32_e32 v23, 0x800000, v23
	v_lshlrev_b32_e32 v106, 16, v86
	v_and_b32_e32 v107, 0xffff0000, v86
	v_lshlrev_b32_e32 v108, 16, v78
	v_and_b32_e32 v109, 0xffff0000, v78
	v_pk_mul_f32 v[106:107], v[96:97], v[106:107] op_sel_hi:[0,1]
	v_pk_fma_f32 v[98:99], v[10:11], v[106:107], v[108:109]
	v_lshlrev_b32_e32 v106, 16, v87
	v_and_b32_e32 v107, 0xffff0000, v87
	v_lshlrev_b32_e32 v108, 16, v79
	v_and_b32_e32 v109, 0xffff0000, v79
	v_pk_mul_f32 v[106:107], v[96:97], v[106:107] op_sel_hi:[0,1]
	v_pk_fma_f32 v[100:101], v[12:13], v[106:107], v[108:109]
	v_lshlrev_b32_e32 v106, 16, v88
	v_and_b32_e32 v107, 0xffff0000, v88
	v_lshlrev_b32_e32 v108, 16, v80
	v_and_b32_e32 v109, 0xffff0000, v80
	v_pk_mul_f32 v[106:107], v[96:97], v[106:107] op_sel_hi:[0,1]
	v_pk_fma_f32 v[102:103], v[14:15], v[106:107], v[108:109]
	v_lshlrev_b32_e32 v106, 16, v89
	v_and_b32_e32 v107, 0xffff0000, v89
	v_lshlrev_b32_e32 v108, 16, v81
	v_and_b32_e32 v109, 0xffff0000, v81
	v_pk_mul_f32 v[106:107], v[96:97], v[106:107] op_sel_hi:[0,1]
	v_pk_fma_f32 v[104:105], v[16:17], v[106:107], v[108:109]
	global_store_dwordx4 v23, v[98:101], s[6:7]
	global_store_dwordx4 v23, v[102:105], s[6:7] offset:16
	v_lshlrev_b32_e32 v106, 16, v90
	v_and_b32_e32 v107, 0xffff0000, v90
	v_lshlrev_b32_e32 v108, 16, v82
	v_and_b32_e32 v109, 0xffff0000, v82
	v_pk_mul_f32 v[106:107], v[96:97], v[106:107] op_sel_hi:[0,1]
	v_pk_fma_f32 v[98:99], v[2:3], v[106:107], v[108:109]
	v_lshlrev_b32_e32 v106, 16, v91
	v_and_b32_e32 v107, 0xffff0000, v91
	v_lshlrev_b32_e32 v108, 16, v83
	v_and_b32_e32 v109, 0xffff0000, v83
	v_pk_mul_f32 v[106:107], v[96:97], v[106:107] op_sel_hi:[0,1]
	v_pk_fma_f32 v[100:101], v[4:5], v[106:107], v[108:109]
	v_lshlrev_b32_e32 v106, 16, v92
	v_and_b32_e32 v107, 0xffff0000, v92
	v_lshlrev_b32_e32 v108, 16, v84
	v_and_b32_e32 v109, 0xffff0000, v84
	v_pk_mul_f32 v[106:107], v[96:97], v[106:107] op_sel_hi:[0,1]
	v_pk_fma_f32 v[102:103], v[6:7], v[106:107], v[108:109]
	v_lshlrev_b32_e32 v106, 16, v93
	v_and_b32_e32 v107, 0xffff0000, v93
	v_lshlrev_b32_e32 v108, 16, v85
	v_and_b32_e32 v109, 0xffff0000, v85
	v_pk_mul_f32 v[106:107], v[96:97], v[106:107] op_sel_hi:[0,1]
	v_pk_fma_f32 v[104:105], v[8:9], v[106:107], v[108:109]
	global_store_dwordx4 v23, v[98:101], s[6:7] offset:2048
	global_store_dwordx4 v23, v[102:105], s[6:7] offset:2064
	v_add_u32_e32 v18, 0x400000, v18
	v_add_u32_e32 v20, 0x400000, v20
	v_add_u32_e32 v21, 0x2000, v21
	global_load_dwordx4 v[78:81], v18, s[4:5]
	global_load_dwordx4 v[86:89], v20, s[6:7]
	global_load_dwordx4 v[82:85], v18, s[4:5] offset:1024
	global_load_dwordx4 v[90:93], v20, s[6:7] offset:1024
	global_load_dword v94, v21, s[4:5]
	s_waitcnt vmcnt(27)
	v_fmamk_f32 v96, v40, 0x3a800000, v244
	v_rsq_f32_e32 v96, v96
	v_add_u32_e32 v19, 0x400000, v19
	v_add_u32_e32 v23, 0x800000, v23
	v_lshlrev_b32_e32 v106, 16, v32
	v_and_b32_e32 v107, 0xffff0000, v32
	v_lshlrev_b32_e32 v108, 16, v24
	v_and_b32_e32 v109, 0xffff0000, v24
	v_pk_mul_f32 v[106:107], v[96:97], v[106:107] op_sel_hi:[0,1]
	v_pk_fma_f32 v[98:99], v[10:11], v[106:107], v[108:109]
	v_lshlrev_b32_e32 v106, 16, v33
	v_and_b32_e32 v107, 0xffff0000, v33
	v_lshlrev_b32_e32 v108, 16, v25
	v_and_b32_e32 v109, 0xffff0000, v25
	v_pk_mul_f32 v[106:107], v[96:97], v[106:107] op_sel_hi:[0,1]
	v_pk_fma_f32 v[100:101], v[12:13], v[106:107], v[108:109]
	v_lshlrev_b32_e32 v106, 16, v34
	v_and_b32_e32 v107, 0xffff0000, v34
	v_lshlrev_b32_e32 v108, 16, v26
	v_and_b32_e32 v109, 0xffff0000, v26
	v_pk_mul_f32 v[106:107], v[96:97], v[106:107] op_sel_hi:[0,1]
	v_pk_fma_f32 v[102:103], v[14:15], v[106:107], v[108:109]
	v_lshlrev_b32_e32 v106, 16, v35
	v_and_b32_e32 v107, 0xffff0000, v35
	v_lshlrev_b32_e32 v108, 16, v27
	v_and_b32_e32 v109, 0xffff0000, v27
	v_pk_mul_f32 v[106:107], v[96:97], v[106:107] op_sel_hi:[0,1]
	v_pk_fma_f32 v[104:105], v[16:17], v[106:107], v[108:109]
	global_store_dwordx4 v23, v[98:101], s[6:7]
	global_store_dwordx4 v23, v[102:105], s[6:7] offset:16
	v_lshlrev_b32_e32 v106, 16, v36
	v_and_b32_e32 v107, 0xffff0000, v36
	v_lshlrev_b32_e32 v108, 16, v28
	v_and_b32_e32 v109, 0xffff0000, v28
	v_pk_mul_f32 v[106:107], v[96:97], v[106:107] op_sel_hi:[0,1]
	v_pk_fma_f32 v[98:99], v[2:3], v[106:107], v[108:109]
	v_lshlrev_b32_e32 v106, 16, v37
	v_and_b32_e32 v107, 0xffff0000, v37
	v_lshlrev_b32_e32 v108, 16, v29
	v_and_b32_e32 v109, 0xffff0000, v29
	v_pk_mul_f32 v[106:107], v[96:97], v[106:107] op_sel_hi:[0,1]
	v_pk_fma_f32 v[100:101], v[4:5], v[106:107], v[108:109]
	v_lshlrev_b32_e32 v106, 16, v38
	v_and_b32_e32 v107, 0xffff0000, v38
	v_lshlrev_b32_e32 v108, 16, v30
	v_and_b32_e32 v109, 0xffff0000, v30
	v_pk_mul_f32 v[106:107], v[96:97], v[106:107] op_sel_hi:[0,1]
	v_pk_fma_f32 v[102:103], v[6:7], v[106:107], v[108:109]
	v_lshlrev_b32_e32 v106, 16, v39
	v_and_b32_e32 v107, 0xffff0000, v39
	v_lshlrev_b32_e32 v108, 16, v31
	v_and_b32_e32 v109, 0xffff0000, v31
	v_pk_mul_f32 v[106:107], v[96:97], v[106:107] op_sel_hi:[0,1]
	v_pk_fma_f32 v[104:105], v[8:9], v[106:107], v[108:109]
	global_store_dwordx4 v23, v[98:101], s[6:7] offset:2048
	global_store_dwordx4 v23, v[102:105], s[6:7] offset:2064
	s_waitcnt vmcnt(22)
; __device__ __forceinline__ float bflo(unsigned w) { return __uint_as_float(w << 16); }
; __device__ __forceinline__ float bfhi(unsigned w) { return __uint_as_float(w & 0xffff0000u); }
; __device__ __forceinline__ void resid_rows(bf16_t* R, const bf16_t* Y, const float* ssqY, const float* g, float* rstd_out, float* outf, bool wf32, int row_lo, int row_hi, int yoff, int gw, int NGW, int lane) {
;     ...
;     for (int row0 = row_lo + gw; row0 < row_hi; row0 += RP * NGW) {
;         u32x4 rr[RP][2], oo[RP][2]; float ssv[RP];
; #pragma unroll
;         for (int k = 0; k < RP; ++k) { const int row = row0 + k * NGW; const bool ok = row < row_hi; const int rw = ok ? row : row0;
;             ssv[k] = ssqY[rw];
; #pragma unroll
;             for (int j = 0; j < 2; ++j) { const int c = 8 * lane + 512 * j; rr[k][j] = *(const u32x4*)(R + (size_t)rw * DM + c); oo[k][j] = *(const u32x4*)(Y + (size_t)(rw - yoff) * DM + c); } }
; #pragma unroll
;         for (int k = 0; k < RP; ++k) { const int row = row0 + k * NGW; if (row < row_hi) {
;             const float rs = __builtin_amdgcn_rsqf(ssv[k] * (1.0f / DM) + RMS_EPS); float s = 0.f;
; #pragma unroll
;             for (int j = 0; j < 2; ++j) { const int c = 8 * lane + 512 * j; const u32x4 r = rr[k][j], o = oo[k][j]; const f32x4 ga = gv[j][0], gb = gv[j][1];
;                 f32x4 ya, yb; ya[0] = bflo(r.x) + bflo(o.x) * rs * ga[0]; ya[1] = bfhi(r.x) + bfhi(o.x) * rs * ga[1]; ya[2] = bflo(r.y) + bflo(o.y) * rs * ga[2]; ya[3] = bfhi(r.y) + bfhi(o.y) * rs * ga[3];
;                 yb[0] = bflo(r.z) + bflo(o.z) * rs * gb[0]; yb[1] = bfhi(r.z) + bfhi(o.z) * rs * gb[1]; yb[2] = bflo(r.w) + bflo(o.w) * rs * gb[2]; yb[3] = bfhi(r.w) + bfhi(o.w) * rs * gb[3];
;                 if (wf32) { *(f32x4*)(outf + (size_t)row * DM + c) = ya; *(f32x4*)(outf + (size_t)row * DM + c + 4) = yb; }
;                 s += (ya[0] * ya[0] + ya[1] * ya[1]) + (ya[2] * ya[2] + ya[3] * ya[3]) + (yb[0] * yb[0] + yb[1] * yb[1]) + (yb[2] * yb[2] + yb[3] * yb[3]);
;                 u32x4 w; w.x = pk2(ya[0], ya[1]); w.y = pk2(ya[2], ya[3]); w.z = pk2(yb[0], yb[1]); w.w = pk2(yb[2], yb[3]); *(u32x4*)(R + (size_t)row * DM + c) = w; }
;             s = wave_sum(s); if (lane == 0) rstd_out[row] = __builtin_amdgcn_rsqf(s * (1.0f / DM) + RMS_EPS); } }
	v_fmamk_f32 v96, v58, 0x3a800000, v244
	v_rsq_f32_e32 v96, v96
	v_add_u32_e32 v19, 0x400000, v19
	v_add_u32_e32 v23, 0x800000, v23
	v_lshlrev_b32_e32 v106, 16, v50
	v_and_b32_e32 v107, 0xffff0000, v50
	v_lshlrev_b32_e32 v108, 16, v42
	v_and_b32_e32 v109, 0xffff0000, v42
	v_pk_mul_f32 v[106:107], v[96:97], v[106:107] op_sel_hi:[0,1]
	v_pk_fma_f32 v[98:99], v[10:11], v[106:107], v[108:109]
	v_lshlrev_b32_e32 v106, 16, v51
	v_and_b32_e32 v107, 0xffff0000, v51
	v_lshlrev_b32_e32 v108, 16, v43
	v_and_b32_e32 v109, 0xffff0000, v43
	v_pk_mul_f32 v[106:107], v[96:97], v[106:107] op_sel_hi:[0,1]
	v_pk_fma_f32 v[100:101], v[12:13], v[106:107], v[108:109]
	v_lshlrev_b32_e32 v106, 16, v52
	v_and_b32_e32 v107, 0xffff0000, v52
	v_lshlrev_b32_e32 v108, 16, v44
	v_and_b32_e32 v109, 0xffff0000, v44
	v_pk_mul_f32 v[106:107], v[96:97], v[106:107] op_sel_hi:[0,1]
	v_pk_fma_f32 v[102:103], v[14:15], v[106:107], v[108:109]
	v_lshlrev_b32_e32 v106, 16, v53
	v_and_b32_e32 v107, 0xffff0000, v53
	v_lshlrev_b32_e32 v108, 16, v45
	v_and_b32_e32 v109, 0xffff0000, v45
	v_pk_mul_f32 v[106:107], v[96:97], v[106:107] op_sel_hi:[0,1]
	v_pk_fma_f32 v[104:105], v[16:17], v[106:107], v[108:109]
	global_store_dwordx4 v23, v[98:101], s[6:7]
	global_store_dwordx4 v23, v[102:105], s[6:7] offset:16
	v_lshlrev_b32_e32 v106, 16, v54
	v_and_b32_e32 v107, 0xffff0000, v54
	v_lshlrev_b32_e32 v108, 16, v46
	v_and_b32_e32 v109, 0xffff0000, v46
	v_pk_mul_f32 v[106:107], v[96:97], v[106:107] op_sel_hi:[0,1]
	v_pk_fma_f32 v[98:99], v[2:3], v[106:107], v[108:109]
	v_lshlrev_b32_e32 v106, 16, v55
	v_and_b32_e32 v107, 0xffff0000, v55
	v_lshlrev_b32_e32 v108, 16, v47
	v_and_b32_e32 v109, 0xffff0000, v47
	v_pk_mul_f32 v[106:107], v[96:97], v[106:107] op_sel_hi:[0,1]
	v_pk_fma_f32 v[100:101], v[4:5], v[106:107], v[108:109]
	v_lshlrev_b32_e32 v106, 16, v56
	v_and_b32_e32 v107, 0xffff0000, v56
	v_lshlrev_b32_e32 v108, 16, v48
	v_and_b32_e32 v109, 0xffff0000, v48
	v_pk_mul_f32 v[106:107], v[96:97], v[106:107] op_sel_hi:[0,1]
	v_pk_fma_f32 v[102:103], v[6:7], v[106:107], v[108:109]
	v_lshlrev_b32_e32 v106, 16, v57
	v_and_b32_e32 v107, 0xffff0000, v57
	v_lshlrev_b32_e32 v108, 16, v49
	v_and_b32_e32 v109, 0xffff0000, v49
	v_pk_mul_f32 v[106:107], v[96:97], v[106:107] op_sel_hi:[0,1]
	v_pk_fma_f32 v[104:105], v[8:9], v[106:107], v[108:109]
	global_store_dwordx4 v23, v[98:101], s[6:7] offset:2048
	global_store_dwordx4 v23, v[102:105], s[6:7] offset:2064
	s_waitcnt vmcnt(17)
; __device__ __forceinline__ float bflo(unsigned w) { return __uint_as_float(w << 16); }
; __device__ __forceinline__ float bfhi(unsigned w) { return __uint_as_float(w & 0xffff0000u); }
; __device__ __forceinline__ void resid_rows(bf16_t* R, const bf16_t* Y, const float* ssqY, const float* g, float* rstd_out, float* outf, bool wf32, int row_lo, int row_hi, int yoff, int gw, int NGW, int lane) {
;     ...
;     for (int row0 = row_lo + gw; row0 < row_hi; row0 += RP * NGW) {
;         u32x4 rr[RP][2], oo[RP][2]; float ssv[RP];
; #pragma unroll
;         for (int k = 0; k < RP; ++k) { const int row = row0 + k * NGW; const bool ok = row < row_hi; const int rw = ok ? row : row0;
;             ssv[k] = ssqY[rw];
; #pragma unroll
;             for (int j = 0; j < 2; ++j) { const int c = 8 * lane + 512 * j; rr[k][j] = *(const u32x4*)(R + (size_t)rw * DM + c); oo[k][j] = *(const u32x4*)(Y + (size_t)(rw - yoff) * DM + c); } }
; #pragma unroll
;         for (int k = 0; k < RP; ++k) { const int row = row0 + k * NGW; if (row < row_hi) {
;             const float rs = __builtin_amdgcn_rsqf(ssv[k] * (1.0f / DM) + RMS_EPS); float s = 0.f;
; #pragma unroll
;             for (int j = 0; j < 2; ++j) { const int c = 8 * lane + 512 * j; const u32x4 r = rr[k][j], o = oo[k][j]; const f32x4 ga = gv[j][0], gb = gv[j][1];
;                 f32x4 ya, yb; ya[0] = bflo(r.x) + bflo(o.x) * rs * ga[0]; ya[1] = bfhi(r.x) + bfhi(o.x) * rs * ga[1]; ya[2] = bflo(r.y) + bflo(o.y) * rs * ga[2]; ya[3] = bfhi(r.y) + bfhi(o.y) * rs * ga[3];
;                 yb[0] = bflo(r.z) + bflo(o.z) * rs * gb[0]; yb[1] = bfhi(r.z) + bfhi(o.z) * rs * gb[1]; yb[2] = bflo(r.w) + bflo(o.w) * rs * gb[2]; yb[3] = bfhi(r.w) + bfhi(o.w) * rs * gb[3];
;                 if (wf32) { *(f32x4*)(outf + (size_t)row * DM + c) = ya; *(f32x4*)(outf + (size_t)row * DM + c + 4) = yb; }
;                 s += (ya[0] * ya[0] + ya[1] * ya[1]) + (ya[2] * ya[2] + ya[3] * ya[3]) + (yb[0] * yb[0] + yb[1] * yb[1]) + (yb[2] * yb[2] + yb[3] * yb[3]);
;                 u32x4 w; w.x = pk2(ya[0], ya[1]); w.y = pk2(ya[2], ya[3]); w.z = pk2(yb[0], yb[1]); w.w = pk2(yb[2], yb[3]); *(u32x4*)(R + (size_t)row * DM + c) = w; }
;             s = wave_sum(s); if (lane == 0) rstd_out[row] = __builtin_amdgcn_rsqf(s * (1.0f / DM) + RMS_EPS); } }
	v_fmamk_f32 v96, v76, 0x3a800000, v244
	v_rsq_f32_e32 v96, v96
	v_add_u32_e32 v19, 0x400000, v19
	v_add_u32_e32 v23, 0x800000, v23
	v_lshlrev_b32_e32 v106, 16, v68
	v_and_b32_e32 v107, 0xffff0000, v68
	v_lshlrev_b32_e32 v108, 16, v60
	v_and_b32_e32 v109, 0xffff0000, v60
	v_pk_mul_f32 v[106:107], v[96:97], v[106:107] op_sel_hi:[0,1]
	v_pk_fma_f32 v[98:99], v[10:11], v[106:107], v[108:109]
	v_lshlrev_b32_e32 v106, 16, v69
	v_and_b32_e32 v107, 0xffff0000, v69
	v_lshlrev_b32_e32 v108, 16, v61
	v_and_b32_e32 v109, 0xffff0000, v61
	v_pk_mul_f32 v[106:107], v[96:97], v[106:107] op_sel_hi:[0,1]
	v_pk_fma_f32 v[100:101], v[12:13], v[106:107], v[108:109]
	v_lshlrev_b32_e32 v106, 16, v70
	v_and_b32_e32 v107, 0xffff0000, v70
	v_lshlrev_b32_e32 v108, 16, v62
	v_and_b32_e32 v109, 0xffff0000, v62
	v_pk_mul_f32 v[106:107], v[96:97], v[106:107] op_sel_hi:[0,1]
	v_pk_fma_f32 v[102:103], v[14:15], v[106:107], v[108:109]
	v_lshlrev_b32_e32 v106, 16, v71
	v_and_b32_e32 v107, 0xffff0000, v71
	v_lshlrev_b32_e32 v108, 16, v63
	v_and_b32_e32 v109, 0xffff0000, v63
	v_pk_mul_f32 v[106:107], v[96:97], v[106:107] op_sel_hi:[0,1]
	v_pk_fma_f32 v[104:105], v[16:17], v[106:107], v[108:109]
	global_store_dwordx4 v23, v[98:101], s[6:7]
	global_store_dwordx4 v23, v[102:105], s[6:7] offset:16
	v_lshlrev_b32_e32 v106, 16, v72
	v_and_b32_e32 v107, 0xffff0000, v72
	v_lshlrev_b32_e32 v108, 16, v64
	v_and_b32_e32 v109, 0xffff0000, v64
	v_pk_mul_f32 v[106:107], v[96:97], v[106:107] op_sel_hi:[0,1]
	v_pk_fma_f32 v[98:99], v[2:3], v[106:107], v[108:109]
	v_lshlrev_b32_e32 v106, 16, v73
	v_and_b32_e32 v107, 0xffff0000, v73
	v_lshlrev_b32_e32 v108, 16, v65
	v_and_b32_e32 v109, 0xffff0000, v65
	v_pk_mul_f32 v[106:107], v[96:97], v[106:107] op_sel_hi:[0,1]
	v_pk_fma_f32 v[100:101], v[4:5], v[106:107], v[108:109]
	v_lshlrev_b32_e32 v106, 16, v74
	v_and_b32_e32 v107, 0xffff0000, v74
	v_lshlrev_b32_e32 v108, 16, v66
	v_and_b32_e32 v109, 0xffff0000, v66
	v_pk_mul_f32 v[106:107], v[96:97], v[106:107] op_sel_hi:[0,1]
	v_pk_fma_f32 v[102:103], v[6:7], v[106:107], v[108:109]
	v_lshlrev_b32_e32 v106, 16, v75
	v_and_b32_e32 v107, 0xffff0000, v75
	v_lshlrev_b32_e32 v108, 16, v67
	v_and_b32_e32 v109, 0xffff0000, v67
	v_pk_mul_f32 v[106:107], v[96:97], v[106:107] op_sel_hi:[0,1]
	v_pk_fma_f32 v[104:105], v[8:9], v[106:107], v[108:109]
	global_store_dwordx4 v23, v[98:101], s[6:7] offset:2048
	global_store_dwordx4 v23, v[102:105], s[6:7] offset:2064
	s_waitcnt vmcnt(12)
	v_fmamk_f32 v96, v94, 0x3a800000, v244
	v_rsq_f32_e32 v96, v96
	v_add_u32_e32 v19, 0x400000, v19
	v_add_u32_e32 v23, 0x800000, v23
	v_lshlrev_b32_e32 v106, 16, v86
	v_and_b32_e32 v107, 0xffff0000, v86
	v_lshlrev_b32_e32 v108, 16, v78
	v_and_b32_e32 v109, 0xffff0000, v78
	v_pk_mul_f32 v[106:107], v[96:97], v[106:107] op_sel_hi:[0,1]
	v_pk_fma_f32 v[98:99], v[10:11], v[106:107], v[108:109]
	v_lshlrev_b32_e32 v106, 16, v87
	v_and_b32_e32 v107, 0xffff0000, v87
	v_lshlrev_b32_e32 v108, 16, v79
	v_and_b32_e32 v109, 0xffff0000, v79
	v_pk_mul_f32 v[106:107], v[96:97], v[106:107] op_sel_hi:[0,1]
	v_pk_fma_f32 v[100:101], v[12:13], v[106:107], v[108:109]
	v_lshlrev_b32_e32 v106, 16, v88
	v_and_b32_e32 v107, 0xffff0000, v88
	v_lshlrev_b32_e32 v108, 16, v80
	v_and_b32_e32 v109, 0xffff0000, v80
	v_pk_mul_f32 v[106:107], v[96:97], v[106:107] op_sel_hi:[0,1]
	v_pk_fma_f32 v[102:103], v[14:15], v[106:107], v[108:109]
	v_lshlrev_b32_e32 v106, 16, v89
	v_and_b32_e32 v107, 0xffff0000, v89
	v_lshlrev_b32_e32 v108, 16, v81
	v_and_b32_e32 v109, 0xffff0000, v81
	v_pk_mul_f32 v[106:107], v[96:97], v[106:107] op_sel_hi:[0,1]
	v_pk_fma_f32 v[104:105], v[16:17], v[106:107], v[108:109]
	global_store_dwordx4 v23, v[98:101], s[6:7]
	global_store_dwordx4 v23, v[102:105], s[6:7] offset:16
	v_lshlrev_b32_e32 v106, 16, v90
	v_and_b32_e32 v107, 0xffff0000, v90
	v_lshlrev_b32_e32 v108, 16, v82
	v_and_b32_e32 v109, 0xffff0000, v82
	v_pk_mul_f32 v[106:107], v[96:97], v[106:107] op_sel_hi:[0,1]
	v_pk_fma_f32 v[98:99], v[2:3], v[106:107], v[108:109]
	v_lshlrev_b32_e32 v106, 16, v91
	v_and_b32_e32 v107, 0xffff0000, v91
	v_lshlrev_b32_e32 v108, 16, v83
	v_and_b32_e32 v109, 0xffff0000, v83
	v_pk_mul_f32 v[106:107], v[96:97], v[106:107] op_sel_hi:[0,1]
	v_pk_fma_f32 v[100:101], v[4:5], v[106:107], v[108:109]
	v_lshlrev_b32_e32 v106, 16, v92
	v_and_b32_e32 v107, 0xffff0000, v92
	v_lshlrev_b32_e32 v108, 16, v84
	v_and_b32_e32 v109, 0xffff0000, v84
	v_pk_mul_f32 v[106:107], v[96:97], v[106:107] op_sel_hi:[0,1]
	v_pk_fma_f32 v[102:103], v[6:7], v[106:107], v[108:109]
	v_lshlrev_b32_e32 v106, 16, v93
	v_and_b32_e32 v107, 0xffff0000, v93
	v_lshlrev_b32_e32 v108, 16, v85
	v_and_b32_e32 v109, 0xffff0000, v85
	v_pk_mul_f32 v[106:107], v[96:97], v[106:107] op_sel_hi:[0,1]
	v_pk_fma_f32 v[104:105], v[8:9], v[106:107], v[108:109]
	global_store_dwordx4 v23, v[98:101], s[6:7] offset:2048
	global_store_dwordx4 v23, v[102:105], s[6:7] offset:2064

; __device__ __forceinline__ void resid_rows(bf16_t* R, const bf16_t* Y, const float* ssqY, const float* g, float* rstd_out, float* outf, bool wf32, int row_lo, int row_hi, int yoff, int gw, int NGW, int lane) {
;     ...
;     for (int row0 = row_lo + gw; row0 < row_hi; row0 += RP * NGW) {
;         u32x4 rr[RP][2], oo[RP][2]; float ssv[RP];
; #pragma unroll
;         for (int k = 0; k < RP; ++k) { const int row = row0 + k * NGW; const bool ok = row < row_hi; const int rw = ok ? row : row0;
;             ssv[k] = ssqY[rw];
; #pragma unroll
;             for (int j = 0; j < 2; ++j) { const int c = 8 * lane + 512 * j; rr[k][j] = *(const u32x4*)(R + (size_t)rw * DM + c); oo[k][j] = *(const u32x4*)(Y + (size_t)(rw - yoff) * DM + c); } }
; #pragma unroll
;         for (int k = 0; k < RP; ++k) { const int row = row0 + k * NGW; if (row < row_hi) {
;             const float rs = __builtin_amdgcn_rsqf(ssv[k] * (1.0f / DM) + RMS_EPS); float s = 0.f;
; #pragma unroll
;             for (int j = 0; j < 2; ++j) { const int c = 8 * lane + 512 * j; const u32x4 r = rr[k][j], o = oo[k][j]; const f32x4 ga = gv[j][0], gb = gv[j][1];
;                 f32x4 ya, yb; ya[0] = bflo(r.x) + bflo(o.x) * rs * ga[0]; ya[1] = bfhi(r.x) + bfhi(o.x) * rs * ga[1]; ya[2] = bflo(r.y) + bflo(o.y) * rs * ga[2]; ya[3] = bfhi(r.y) + bfhi(o.y) * rs * ga[3];
;                 yb[0] = bflo(r.z) + bflo(o.z) * rs * gb[0]; yb[1] = bfhi(r.z) + bfhi(o.z) * rs * gb[1]; yb[2] = bflo(r.w) + bflo(o.w) * rs * gb[2]; yb[3] = bfhi(r.w) + bfhi(o.w) * rs * gb[3];
;                 if (wf32) { *(f32x4*)(outf + (size_t)row * DM + c) = ya; *(f32x4*)(outf + (size_t)row * DM + c + 4) = yb; }
;                 s += (ya[0] * ya[0] + ya[1] * ya[1]) + (ya[2] * ya[2] + ya[3] * ya[3]) + (yb[0] * yb[0] + yb[1] * yb[1]) + (yb[2] * yb[2] + yb[3] * yb[3]);
;                 u32x4 w; w.x = pk2(ya[0], ya[1]); w.y = pk2(ya[2], ya[3]); w.z = pk2(yb[0], yb[1]); w.w = pk2(yb[2], yb[3]); *(u32x4*)(R + (size_t)row * DM + c) = w; }
;             s = wave_sum(s); if (lane == 0) rstd_out[row] = __builtin_amdgcn_rsqf(s * (1.0f / DM) + RMS_EPS); } }
; __global__ void __launch_bounds__(512, 2) fwd_megakernel(Params P) {
;     ...
;         if (EN(7) && IN(pb + 8)) {
;             const bool lastl = (l == NLAYER - 1);
;             { const int lane = otid() & 63, gw = bx * 8 + (otid() >> 6);
.LBB0_877:
	v_mov_b32_e32 v2, v0
	v_mov_b32_e32 v3, v0
	v_readlane_b32 s4, v255, 4
	v_ashrrev_i32_e32 v18, 6, v3
	s_mov_b64 s[6:7], s[0:1]
	v_add_u32_e32 v86, s4, v18
	s_mov_b64 s[4:5], s[0:1]
	s_mov_b64 s[10:11], s[0:1]
	s_mov_b64 s[12:13], s[0:1]
	s_mov_b64 s[8:9], s[0:1]
	v_cmp_gt_i32_e32 vcc, s47, v86
	s_and_saveexec_b64 s[16:17], vcc
	s_cbranch_execz .LBB0_907
	v_readlane_b32 s12, v255, 49
	s_cmp_eq_u32 s12, 1
	s_cbranch_scc0 .LBB0_907
	v_lshrrev_b32_e32 v114, 6, v0
	v_readlane_b32 s12, v255, 49
	v_readlane_b32 s13, v255, 4
	v_readfirstlane_b32 s18, v114
	s_load_dwordx2 s[4:5], s[0:1], 0x98
	s_load_dwordx2 s[10:11], s[0:1], 0x68
	s_load_dwordx2 s[6:7], s[0:1], 0x90
	s_add_i32 s13, s13, s18
	v_and_b32_e32 v115, 63, v0
	v_lshlrev_b32_e32 v114, 4, v115
	v_lshlrev_b32_e32 v115, 5, v115
	s_lshl_b32 s18, s12, 12
	s_lshl_b32 s19, s12, 18
	s_bfm_b64 s[8:9], 1, 63
	s_waitcnt lgkmcnt(0)
	s_add_u32 s10, s10, s18
	s_addc_u32 s11, s11, 0
	global_load_dwordx4 v[2:5], v115, s[10:11] offset:2048
	global_load_dwordx4 v[6:9], v115, s[10:11] offset:2064
	global_load_dwordx4 v[10:13], v115, s[10:11]
	global_load_dwordx4 v[14:17], v115, s[10:11] offset:16
	s_lshl_b32 s18, s13, 11
	v_add_u32_e32 v18, s18, v114
	v_mov_b32_e32 v19, v18
	v_mov_b32_e32 v20, v18
	s_lshl_b32 s18, s13, 2
	v_mov_b32_e32 v22, s18
	s_add_i32 s18, s18, s19
	v_mov_b32_e32 v21, s18
	s_lshl_b32 s18, s13, 12
	v_add_u32_e32 v23, s18, v115
	v_add_u32_e32 v18, 0x3001000, v18
	v_add_u32_e32 v20, 0xd000000, v20
	v_add_u32_e32 v21, 0x2d60000, v21
	global_load_dwordx4 v[24:27], v18, s[4:5]
	global_load_dwordx4 v[32:35], v20, s[4:5]
	global_load_dwordx4 v[28:31], v18, s[4:5] offset:1024
	global_load_dwordx4 v[36:39], v20, s[4:5] offset:1024
	global_load_dword v40, v21, s[4:5]
	v_add_u32_e32 v18, 0x400000, v18
	v_add_u32_e32 v20, 0x400000, v20
	v_add_u32_e32 v21, 0x2000, v21
	global_load_dwordx4 v[42:45], v18, s[4:5]
	global_load_dwordx4 v[50:53], v20, s[4:5]
	global_load_dwordx4 v[46:49], v18, s[4:5] offset:1024
	global_load_dwordx4 v[54:57], v20, s[4:5] offset:1024
	global_load_dword v58, v21, s[4:5]
	v_add_u32_e32 v18, 0x400000, v18
	v_add_u32_e32 v20, 0x400000, v20
	v_add_u32_e32 v21, 0x2000, v21
	global_load_dwordx4 v[60:63], v18, s[4:5]
	global_load_dwordx4 v[68:71], v20, s[4:5]
	global_load_dwordx4 v[64:67], v18, s[4:5] offset:1024
	global_load_dwordx4 v[72:75], v20, s[4:5] offset:1024
	global_load_dword v76, v21, s[4:5]
	v_add_u32_e32 v18, 0x400000, v18
	v_add_u32_e32 v20, 0x400000, v20
	v_add_u32_e32 v21, 0x2000, v21
	global_load_dwordx4 v[78:81], v18, s[4:5]
	global_load_dwordx4 v[86:89], v20, s[4:5]
	global_load_dwordx4 v[82:85], v18, s[4:5] offset:1024
	global_load_dwordx4 v[90:93], v20, s[4:5] offset:1024
	global_load_dword v94, v21, s[4:5]
	s_waitcnt vmcnt(15)
	v_fmamk_f32 v96, v40, 0x3a800000, v244
	v_rsq_f32_e32 v96, v96
	v_add_u32_e32 v19, 0x3001000, v19
	v_lshlrev_b32_e32 v106, 16, v32
	v_and_b32_e32 v107, 0xffff0000, v32
	v_lshlrev_b32_e32 v108, 16, v24
	v_and_b32_e32 v109, 0xffff0000, v24
	v_pk_mul_f32 v[106:107], v[96:97], v[106:107] op_sel_hi:[0,1]
	v_pk_fma_f32 v[98:99], v[10:11], v[106:107], v[108:109]
	v_lshlrev_b32_e32 v106, 16, v33
	v_and_b32_e32 v107, 0xffff0000, v33
	v_lshlrev_b32_e32 v108, 16, v25
	v_and_b32_e32 v109, 0xffff0000, v25
	v_pk_mul_f32 v[106:107], v[96:97], v[106:107] op_sel_hi:[0,1]
	v_pk_fma_f32 v[100:101], v[12:13], v[106:107], v[108:109]
	v_lshlrev_b32_e32 v106, 16, v34
	v_and_b32_e32 v107, 0xffff0000, v34
	v_lshlrev_b32_e32 v108, 16, v26
	v_and_b32_e32 v109, 0xffff0000, v26
	v_pk_mul_f32 v[106:107], v[96:97], v[106:107] op_sel_hi:[0,1]
	v_pk_fma_f32 v[102:103], v[14:15], v[106:107], v[108:109]
	v_lshlrev_b32_e32 v106, 16, v35
	v_and_b32_e32 v107, 0xffff0000, v35
	v_lshlrev_b32_e32 v108, 16, v27
	v_and_b32_e32 v109, 0xffff0000, v27
	v_pk_mul_f32 v[106:107], v[96:97], v[106:107] op_sel_hi:[0,1]
	v_pk_fma_f32 v[104:105], v[16:17], v[106:107], v[108:109]
	global_store_dwordx4 v23, v[98:101], s[6:7]
	global_store_dwordx4 v23, v[102:105], s[6:7] offset:16
	v_lshlrev_b32_e32 v106, 16, v36
	v_and_b32_e32 v107, 0xffff0000, v36
	v_lshlrev_b32_e32 v108, 16, v28
	v_and_b32_e32 v109, 0xffff0000, v28
	v_pk_mul_f32 v[106:107], v[96:97], v[106:107] op_sel_hi:[0,1]
	v_pk_fma_f32 v[98:99], v[2:3], v[106:107], v[108:109]
	v_lshlrev_b32_e32 v106, 16, v37
	v_and_b32_e32 v107, 0xffff0000, v37
	v_lshlrev_b32_e32 v108, 16, v29
	v_and_b32_e32 v109, 0xffff0000, v29
	v_pk_mul_f32 v[106:107], v[96:97], v[106:107] op_sel_hi:[0,1]
	v_pk_fma_f32 v[100:101], v[4:5], v[106:107], v[108:109]
	v_lshlrev_b32_e32 v106, 16, v38
	v_and_b32_e32 v107, 0xffff0000, v38
	v_lshlrev_b32_e32 v108, 16, v30
	v_and_b32_e32 v109, 0xffff0000, v30
	v_pk_mul_f32 v[106:107], v[96:97], v[106:107] op_sel_hi:[0,1]
	v_pk_fma_f32 v[102:103], v[6:7], v[106:107], v[108:109]
	v_lshlrev_b32_e32 v106, 16, v39
	v_and_b32_e32 v107, 0xffff0000, v39
	v_lshlrev_b32_e32 v108, 16, v31
	v_and_b32_e32 v109, 0xffff0000, v31
	v_pk_mul_f32 v[106:107], v[96:97], v[106:107] op_sel_hi:[0,1]
	v_pk_fma_f32 v[104:105], v[8:9], v[106:107], v[108:109]
	global_store_dwordx4 v23, v[98:101], s[6:7] offset:2048
	global_store_dwordx4 v23, v[102:105], s[6:7] offset:2064
	v_add_u32_e32 v18, 0x400000, v18
	v_add_u32_e32 v20, 0x400000, v20
	v_add_u32_e32 v21, 0x2000, v21
	global_load_dwordx4 v[24:27], v18, s[4:5]
	global_load_dwordx4 v[32:35], v20, s[4:5]
	global_load_dwordx4 v[28:31], v18, s[4:5] offset:1024
	global_load_dwordx4 v[36:39], v20, s[4:5] offset:1024
	global_load_dword v40, v21, s[4:5]
	s_waitcnt vmcnt(19)
; __device__ __forceinline__ float bflo(unsigned w) { return __uint_as_float(w << 16); }
; __device__ __forceinline__ float bfhi(unsigned w) { return __uint_as_float(w & 0xffff0000u); }
; __device__ __forceinline__ void resid_rows(bf16_t* R, const bf16_t* Y, const float* ssqY, const float* g, float* rstd_out, float* outf, bool wf32, int row_lo, int row_hi, int yoff, int gw, int NGW, int lane) {
;     ...
;     for (int row0 = row_lo + gw; row0 < row_hi; row0 += RP * NGW) {
;         u32x4 rr[RP][2], oo[RP][2]; float ssv[RP];
; #pragma unroll
;         for (int k = 0; k < RP; ++k) { const int row = row0 + k * NGW; const bool ok = row < row_hi; const int rw = ok ? row : row0;
;             ssv[k] = ssqY[rw];
; #pragma unroll
;             for (int j = 0; j < 2; ++j) { const int c = 8 * lane + 512 * j; rr[k][j] = *(const u32x4*)(R + (size_t)rw * DM + c); oo[k][j] = *(const u32x4*)(Y + (size_t)(rw - yoff) * DM + c); } }
; #pragma unroll
;         for (int k = 0; k < RP; ++k) { const int row = row0 + k * NGW; if (row < row_hi) {
;             const float rs = __builtin_amdgcn_rsqf(ssv[k] * (1.0f / DM) + RMS_EPS); float s = 0.f;
; #pragma unroll
;             for (int j = 0; j < 2; ++j) { const int c = 8 * lane + 512 * j; const u32x4 r = rr[k][j], o = oo[k][j]; const f32x4 ga = gv[j][0], gb = gv[j][1];
;                 f32x4 ya, yb; ya[0] = bflo(r.x) + bflo(o.x) * rs * ga[0]; ya[1] = bfhi(r.x) + bfhi(o.x) * rs * ga[1]; ya[2] = bflo(r.y) + bflo(o.y) * rs * ga[2]; ya[3] = bfhi(r.y) + bfhi(o.y) * rs * ga[3];
;                 yb[0] = bflo(r.z) + bflo(o.z) * rs * gb[0]; yb[1] = bfhi(r.z) + bfhi(o.z) * rs * gb[1]; yb[2] = bflo(r.w) + bflo(o.w) * rs * gb[2]; yb[3] = bfhi(r.w) + bfhi(o.w) * rs * gb[3];
;                 if (wf32) { *(f32x4*)(outf + (size_t)row * DM + c) = ya; *(f32x4*)(outf + (size_t)row * DM + c + 4) = yb; }
;                 s += (ya[0] * ya[0] + ya[1] * ya[1]) + (ya[2] * ya[2] + ya[3] * ya[3]) + (yb[0] * yb[0] + yb[1] * yb[1]) + (yb[2] * yb[2] + yb[3] * yb[3]);
;                 u32x4 w; w.x = pk2(ya[0], ya[1]); w.y = pk2(ya[2], ya[3]); w.z = pk2(yb[0], yb[1]); w.w = pk2(yb[2], yb[3]); *(u32x4*)(R + (size_t)row * DM + c) = w; }
;             s = wave_sum(s); if (lane == 0) rstd_out[row] = __builtin_amdgcn_rsqf(s * (1.0f / DM) + RMS_EPS); } }
	v_fmamk_f32 v96, v58, 0x3a800000, v244
	v_rsq_f32_e32 v96, v96
	v_add_u32_e32 v19, 0x400000, v19
	v_add_u32_e32 v23, 0x800000, v23
	v_lshlrev_b32_e32 v106, 16, v50
	v_and_b32_e32 v107, 0xffff0000, v50
	v_lshlrev_b32_e32 v108, 16, v42
	v_and_b32_e32 v109, 0xffff0000, v42
	v_pk_mul_f32 v[106:107], v[96:97], v[106:107] op_sel_hi:[0,1]
	v_pk_fma_f32 v[98:99], v[10:11], v[106:107], v[108:109]
	v_lshlrev_b32_e32 v106, 16, v51
	v_and_b32_e32 v107, 0xffff0000, v51
	v_lshlrev_b32_e32 v108, 16, v43
	v_and_b32_e32 v109, 0xffff0000, v43
	v_pk_mul_f32 v[106:107], v[96:97], v[106:107] op_sel_hi:[0,1]
	v_pk_fma_f32 v[100:101], v[12:13], v[106:107], v[108:109]
	v_lshlrev_b32_e32 v106, 16, v52
	v_and_b32_e32 v107, 0xffff0000, v52
	v_lshlrev_b32_e32 v108, 16, v44
	v_and_b32_e32 v109, 0xffff0000, v44
	v_pk_mul_f32 v[106:107], v[96:97], v[106:107] op_sel_hi:[0,1]
	v_pk_fma_f32 v[102:103], v[14:15], v[106:107], v[108:109]
	v_lshlrev_b32_e32 v106, 16, v53
	v_and_b32_e32 v107, 0xffff0000, v53
	v_lshlrev_b32_e32 v108, 16, v45
	v_and_b32_e32 v109, 0xffff0000, v45
	v_pk_mul_f32 v[106:107], v[96:97], v[106:107] op_sel_hi:[0,1]
	v_pk_fma_f32 v[104:105], v[16:17], v[106:107], v[108:109]
	global_store_dwordx4 v23, v[98:101], s[6:7]
	global_store_dwordx4 v23, v[102:105], s[6:7] offset:16
	v_lshlrev_b32_e32 v106, 16, v54
	v_and_b32_e32 v107, 0xffff0000, v54
	v_lshlrev_b32_e32 v108, 16, v46
	v_and_b32_e32 v109, 0xffff0000, v46
	v_pk_mul_f32 v[106:107], v[96:97], v[106:107] op_sel_hi:[0,1]
	v_pk_fma_f32 v[98:99], v[2:3], v[106:107], v[108:109]
	v_lshlrev_b32_e32 v106, 16, v55
	v_and_b32_e32 v107, 0xffff0000, v55
	v_lshlrev_b32_e32 v108, 16, v47
	v_and_b32_e32 v109, 0xffff0000, v47
	v_pk_mul_f32 v[106:107], v[96:97], v[106:107] op_sel_hi:[0,1]
	v_pk_fma_f32 v[100:101], v[4:5], v[106:107], v[108:109]
	v_lshlrev_b32_e32 v106, 16, v56
	v_and_b32_e32 v107, 0xffff0000, v56
	v_lshlrev_b32_e32 v108, 16, v48
	v_and_b32_e32 v109, 0xffff0000, v48
	v_pk_mul_f32 v[106:107], v[96:97], v[106:107] op_sel_hi:[0,1]
	v_pk_fma_f32 v[102:103], v[6:7], v[106:107], v[108:109]
	v_lshlrev_b32_e32 v106, 16, v57
	v_and_b32_e32 v107, 0xffff0000, v57
	v_lshlrev_b32_e32 v108, 16, v49
	v_and_b32_e32 v109, 0xffff0000, v49
	v_pk_mul_f32 v[106:107], v[96:97], v[106:107] op_sel_hi:[0,1]
	v_pk_fma_f32 v[104:105], v[8:9], v[106:107], v[108:109]
	global_store_dwordx4 v23, v[98:101], s[6:7] offset:2048
	global_store_dwordx4 v23, v[102:105], s[6:7] offset:2064
	v_add_u32_e32 v18, 0x400000, v18
	v_add_u32_e32 v20, 0x400000, v20
	v_add_u32_e32 v21, 0x2000, v21
	global_load_dwordx4 v[42:45], v18, s[4:5]
	global_load_dwordx4 v[50:53], v20, s[4:5]
	global_load_dwordx4 v[46:49], v18, s[4:5] offset:1024
	global_load_dwordx4 v[54:57], v20, s[4:5] offset:1024
	global_load_dword v58, v21, s[4:5]
	s_waitcnt vmcnt(23)
	v_fmamk_f32 v96, v76, 0x3a800000, v244
	v_rsq_f32_e32 v96, v96
	v_add_u32_e32 v19, 0x400000, v19
	v_add_u32_e32 v23, 0x800000, v23
	v_lshlrev_b32_e32 v106, 16, v68
	v_and_b32_e32 v107, 0xffff0000, v68
	v_lshlrev_b32_e32 v108, 16, v60
	v_and_b32_e32 v109, 0xffff0000, v60
	v_pk_mul_f32 v[106:107], v[96:97], v[106:107] op_sel_hi:[0,1]
	v_pk_fma_f32 v[98:99], v[10:11], v[106:107], v[108:109]
	v_lshlrev_b32_e32 v106, 16, v69
	v_and_b32_e32 v107, 0xffff0000, v69
	v_lshlrev_b32_e32 v108, 16, v61
	v_and_b32_e32 v109, 0xffff0000, v61
	v_pk_mul_f32 v[106:107], v[96:97], v[106:107] op_sel_hi:[0,1]
	v_pk_fma_f32 v[100:101], v[12:13], v[106:107], v[108:109]
	v_lshlrev_b32_e32 v106, 16, v70
	v_and_b32_e32 v107, 0xffff0000, v70
	v_lshlrev_b32_e32 v108, 16, v62
	v_and_b32_e32 v109, 0xffff0000, v62
	v_pk_mul_f32 v[106:107], v[96:97], v[106:107] op_sel_hi:[0,1]
	v_pk_fma_f32 v[102:103], v[14:15], v[106:107], v[108:109]
	v_lshlrev_b32_e32 v106, 16, v71
	v_and_b32_e32 v107, 0xffff0000, v71
	v_lshlrev_b32_e32 v108, 16, v63
	v_and_b32_e32 v109, 0xffff0000, v63
	v_pk_mul_f32 v[106:107], v[96:97], v[106:107] op_sel_hi:[0,1]
	v_pk_fma_f32 v[104:105], v[16:17], v[106:107], v[108:109]
	global_store_dwordx4 v23, v[98:101], s[6:7]
	global_store_dwordx4 v23, v[102:105], s[6:7] offset:16
	v_lshlrev_b32_e32 v106, 16, v72
	v_and_b32_e32 v107, 0xffff0000, v72
	v_lshlrev_b32_e32 v108, 16, v64
	v_and_b32_e32 v109, 0xffff0000, v64
	v_pk_mul_f32 v[106:107], v[96:97], v[106:107] op_sel_hi:[0,1]
	v_pk_fma_f32 v[98:99], v[2:3], v[106:107], v[108:109]
	v_lshlrev_b32_e32 v106, 16, v73
	v_and_b32_e32 v107, 0xffff0000, v73
	v_lshlrev_b32_e32 v108, 16, v65
	v_and_b32_e32 v109, 0xffff0000, v65
	v_pk_mul_f32 v[106:107], v[96:97], v[106:107] op_sel_hi:[0,1]
	v_pk_fma_f32 v[100:101], v[4:5], v[106:107], v[108:109]
	v_lshlrev_b32_e32 v106, 16, v74
	v_and_b32_e32 v107, 0xffff0000, v74
	v_lshlrev_b32_e32 v108, 16, v66
	v_and_b32_e32 v109, 0xffff0000, v66
	v_pk_mul_f32 v[106:107], v[96:97], v[106:107] op_sel_hi:[0,1]
	v_pk_fma_f32 v[102:103], v[6:7], v[106:107], v[108:109]
	v_lshlrev_b32_e32 v106, 16, v75
	v_and_b32_e32 v107, 0xffff0000, v75
	v_lshlrev_b32_e32 v108, 16, v67
	v_and_b32_e32 v109, 0xffff0000, v67
	v_pk_mul_f32 v[106:107], v[96:97], v[106:107] op_sel_hi:[0,1]
	v_pk_fma_f32 v[104:105], v[8:9], v[106:107], v[108:109]
	global_store_dwordx4 v23, v[98:101], s[6:7] offset:2048
	global_store_dwordx4 v23, v[102:105], s[6:7] offset:2064
	v_add_u32_e32 v18, 0x400000, v18
	v_add_u32_e32 v20, 0x400000, v20
	v_add_u32_e32 v21, 0x2000, v21
	global_load_dwordx4 v[60:63], v18, s[4:5]
	global_load_dwordx4 v[68:71], v20, s[4:5]
	global_load_dwordx4 v[64:67], v18, s[4:5] offset:1024
	global_load_dwordx4 v[72:75], v20, s[4:5] offset:1024
	global_load_dword v76, v21, s[4:5]
	s_waitcnt vmcnt(27)
; __device__ __forceinline__ float bflo(unsigned w) { return __uint_as_float(w << 16); }
; __device__ __forceinline__ float bfhi(unsigned w) { return __uint_as_float(w & 0xffff0000u); }
; __device__ __forceinline__ void resid_rows(bf16_t* R, const bf16_t* Y, const float* ssqY, const float* g, float* rstd_out, float* outf, bool wf32, int row_lo, int row_hi, int yoff, int gw, int NGW, int lane) {
;     ...
;     for (int row0 = row_lo + gw; row0 < row_hi; row0 += RP * NGW) {
;         u32x4 rr[RP][2], oo[RP][2]; float ssv[RP];
; #pragma unroll
;         for (int k = 0; k < RP; ++k) { const int row = row0 + k * NGW; const bool ok = row < row_hi; const int rw = ok ? row : row0;
;             ssv[k] = ssqY[rw];
; #pragma unroll
;             for (int j = 0; j < 2; ++j) { const int c = 8 * lane + 512 * j; rr[k][j] = *(const u32x4*)(R + (size_t)rw * DM + c); oo[k][j] = *(const u32x4*)(Y + (size_t)(rw - yoff) * DM + c); } }
; #pragma unroll
;         for (int k = 0; k < RP; ++k) { const int row = row0 + k * NGW; if (row < row_hi) {
;             const float rs = __builtin_amdgcn_rsqf(ssv[k] * (1.0f / DM) + RMS_EPS); float s = 0.f;
; #pragma unroll
;             for (int j = 0; j < 2; ++j) { const int c = 8 * lane + 512 * j; const u32x4 r = rr[k][j], o = oo[k][j]; const f32x4 ga = gv[j][0], gb = gv[j][1];
;                 f32x4 ya, yb; ya[0] = bflo(r.x) + bflo(o.x) * rs * ga[0]; ya[1] = bfhi(r.x) + bfhi(o.x) * rs * ga[1]; ya[2] = bflo(r.y) + bflo(o.y) * rs * ga[2]; ya[3] = bfhi(r.y) + bfhi(o.y) * rs * ga[3];
;                 yb[0] = bflo(r.z) + bflo(o.z) * rs * gb[0]; yb[1] = bfhi(r.z) + bfhi(o.z) * rs * gb[1]; yb[2] = bflo(r.w) + bflo(o.w) * rs * gb[2]; yb[3] = bfhi(r.w) + bfhi(o.w) * rs * gb[3];
;                 if (wf32) { *(f32x4*)(outf + (size_t)row * DM + c) = ya; *(f32x4*)(outf + (size_t)row * DM + c + 4) = yb; }
;                 s += (ya[0] * ya[0] + ya[1] * ya[1]) + (ya[2] * ya[2] + ya[3] * ya[3]) + (yb[0] * yb[0] + yb[1] * yb[1]) + (yb[2] * yb[2] + yb[3] * yb[3]);
;                 u32x4 w; w.x = pk2(ya[0], ya[1]); w.y = pk2(ya[2], ya[3]); w.z = pk2(yb[0], yb[1]); w.w = pk2(yb[2], yb[3]); *(u32x4*)(R + (size_t)row * DM + c) = w; }
;             s = wave_sum(s); if (lane == 0) rstd_out[row] = __builtin_amdgcn_rsqf(s * (1.0f / DM) + RMS_EPS); } }
	v_fmamk_f32 v96, v94, 0x3a800000, v244
	v_rsq_f32_e32 v96, v96
	v_add_u32_e32 v19, 0x400000, v19
	v_add_u32_e32 v23, 0x800000, v23
	v_lshlrev_b32_e32 v106, 16, v86
	v_and_b32_e32 v107, 0xffff0000, v86
	v_lshlrev_b32_e32 v108, 16, v78
	v_and_b32_e32 v109, 0xffff0000, v78
	v_pk_mul_f32 v[106:107], v[96:97], v[106:107] op_sel_hi:[0,1]
	v_pk_fma_f32 v[98:99], v[10:11], v[106:107], v[108:109]
	v_lshlrev_b32_e32 v106, 16, v87
	v_and_b32_e32 v107, 0xffff0000, v87
	v_lshlrev_b32_e32 v108, 16, v79
	v_and_b32_e32 v109, 0xffff0000, v79
	v_pk_mul_f32 v[106:107], v[96:97], v[106:107] op_sel_hi:[0,1]
	v_pk_fma_f32 v[100:101], v[12:13], v[106:107], v[108:109]
	v_lshlrev_b32_e32 v106, 16, v88
	v_and_b32_e32 v107, 0xffff0000, v88
	v_lshlrev_b32_e32 v108, 16, v80
	v_and_b32_e32 v109, 0xffff0000, v80
	v_pk_mul_f32 v[106:107], v[96:97], v[106:107] op_sel_hi:[0,1]
	v_pk_fma_f32 v[102:103], v[14:15], v[106:107], v[108:109]
	v_lshlrev_b32_e32 v106, 16, v89
	v_and_b32_e32 v107, 0xffff0000, v89
	v_lshlrev_b32_e32 v108, 16, v81
	v_and_b32_e32 v109, 0xffff0000, v81
	v_pk_mul_f32 v[106:107], v[96:97], v[106:107] op_sel_hi:[0,1]
	v_pk_fma_f32 v[104:105], v[16:17], v[106:107], v[108:109]
	global_store_dwordx4 v23, v[98:101], s[6:7]
	global_store_dwordx4 v23, v[102:105], s[6:7] offset:16
	v_lshlrev_b32_e32 v106, 16, v90
	v_and_b32_e32 v107, 0xffff0000, v90
	v_lshlrev_b32_e32 v108, 16, v82
	v_and_b32_e32 v109, 0xffff0000, v82
	v_pk_mul_f32 v[106:107], v[96:97], v[106:107] op_sel_hi:[0,1]
	v_pk_fma_f32 v[98:99], v[2:3], v[106:107], v[108:109]
	v_lshlrev_b32_e32 v106, 16, v91
	v_and_b32_e32 v107, 0xffff0000, v91
	v_lshlrev_b32_e32 v108, 16, v83
	v_and_b32_e32 v109, 0xffff0000, v83
	v_pk_mul_f32 v[106:107], v[96:97], v[106:107] op_sel_hi:[0,1]
	v_pk_fma_f32 v[100:101], v[4:5], v[106:107], v[108:109]
	v_lshlrev_b32_e32 v106, 16, v92
	v_and_b32_e32 v107, 0xffff0000, v92
	v_lshlrev_b32_e32 v108, 16, v84
	v_and_b32_e32 v109, 0xffff0000, v84
	v_pk_mul_f32 v[106:107], v[96:97], v[106:107] op_sel_hi:[0,1]
	v_pk_fma_f32 v[102:103], v[6:7], v[106:107], v[108:109]
	v_lshlrev_b32_e32 v106, 16, v93
	v_and_b32_e32 v107, 0xffff0000, v93
	v_lshlrev_b32_e32 v108, 16, v85
	v_and_b32_e32 v109, 0xffff0000, v85
	v_pk_mul_f32 v[106:107], v[96:97], v[106:107] op_sel_hi:[0,1]
	v_pk_fma_f32 v[104:105], v[8:9], v[106:107], v[108:109]
	global_store_dwordx4 v23, v[98:101], s[6:7] offset:2048
	global_store_dwordx4 v23, v[102:105], s[6:7] offset:2064
	v_add_u32_e32 v18, 0x400000, v18
	v_add_u32_e32 v20, 0x400000, v20
	v_add_u32_e32 v21, 0x2000, v21
	global_load_dwordx4 v[78:81], v18, s[4:5]
	global_load_dwordx4 v[86:89], v20, s[4:5]
	global_load_dwordx4 v[82:85], v18, s[4:5] offset:1024
	global_load_dwordx4 v[90:93], v20, s[4:5] offset:1024
	global_load_dword v94, v21, s[4:5]
	s_waitcnt vmcnt(27)
	v_fmamk_f32 v96, v40, 0x3a800000, v244
	v_rsq_f32_e32 v96, v96
	v_add_u32_e32 v19, 0x400000, v19
	v_add_u32_e32 v23, 0x800000, v23
	v_lshlrev_b32_e32 v106, 16, v32
	v_and_b32_e32 v107, 0xffff0000, v32
	v_lshlrev_b32_e32 v108, 16, v24
	v_and_b32_e32 v109, 0xffff0000, v24
	v_pk_mul_f32 v[106:107], v[96:97], v[106:107] op_sel_hi:[0,1]
	v_pk_fma_f32 v[98:99], v[10:11], v[106:107], v[108:109]
	v_lshlrev_b32_e32 v106, 16, v33
	v_and_b32_e32 v107, 0xffff0000, v33
	v_lshlrev_b32_e32 v108, 16, v25
	v_and_b32_e32 v109, 0xffff0000, v25
	v_pk_mul_f32 v[106:107], v[96:97], v[106:107] op_sel_hi:[0,1]
	v_pk_fma_f32 v[100:101], v[12:13], v[106:107], v[108:109]
	v_lshlrev_b32_e32 v106, 16, v34
	v_and_b32_e32 v107, 0xffff0000, v34
	v_lshlrev_b32_e32 v108, 16, v26
	v_and_b32_e32 v109, 0xffff0000, v26
	v_pk_mul_f32 v[106:107], v[96:97], v[106:107] op_sel_hi:[0,1]
	v_pk_fma_f32 v[102:103], v[14:15], v[106:107], v[108:109]
	v_lshlrev_b32_e32 v106, 16, v35
	v_and_b32_e32 v107, 0xffff0000, v35
	v_lshlrev_b32_e32 v108, 16, v27
	v_and_b32_e32 v109, 0xffff0000, v27
	v_pk_mul_f32 v[106:107], v[96:97], v[106:107] op_sel_hi:[0,1]
	v_pk_fma_f32 v[104:105], v[16:17], v[106:107], v[108:109]
	global_store_dwordx4 v23, v[98:101], s[6:7]
	global_store_dwordx4 v23, v[102:105], s[6:7] offset:16
	v_lshlrev_b32_e32 v106, 16, v36
	v_and_b32_e32 v107, 0xffff0000, v36
	v_lshlrev_b32_e32 v108, 16, v28
	v_and_b32_e32 v109, 0xffff0000, v28
	v_pk_mul_f32 v[106:107], v[96:97], v[106:107] op_sel_hi:[0,1]
	v_pk_fma_f32 v[98:99], v[2:3], v[106:107], v[108:109]
	v_lshlrev_b32_e32 v106, 16, v37
	v_and_b32_e32 v107, 0xffff0000, v37
	v_lshlrev_b32_e32 v108, 16, v29
	v_and_b32_e32 v109, 0xffff0000, v29
	v_pk_mul_f32 v[106:107], v[96:97], v[106:107] op_sel_hi:[0,1]
	v_pk_fma_f32 v[100:101], v[4:5], v[106:107], v[108:109]
	v_lshlrev_b32_e32 v106, 16, v38
	v_and_b32_e32 v107, 0xffff0000, v38
	v_lshlrev_b32_e32 v108, 16, v30
	v_and_b32_e32 v109, 0xffff0000, v30
	v_pk_mul_f32 v[106:107], v[96:97], v[106:107] op_sel_hi:[0,1]
	v_pk_fma_f32 v[102:103], v[6:7], v[106:107], v[108:109]
	v_lshlrev_b32_e32 v106, 16, v39
	v_and_b32_e32 v107, 0xffff0000, v39
	v_lshlrev_b32_e32 v108, 16, v31
	v_and_b32_e32 v109, 0xffff0000, v31
	v_pk_mul_f32 v[106:107], v[96:97], v[106:107] op_sel_hi:[0,1]
	v_pk_fma_f32 v[104:105], v[8:9], v[106:107], v[108:109]
	global_store_dwordx4 v23, v[98:101], s[6:7] offset:2048
	global_store_dwordx4 v23, v[102:105], s[6:7] offset:2064
	s_waitcnt vmcnt(22)
; __device__ __forceinline__ float bflo(unsigned w) { return __uint_as_float(w << 16); }
; __device__ __forceinline__ float bfhi(unsigned w) { return __uint_as_float(w & 0xffff0000u); }
; __device__ __forceinline__ void resid_rows(bf16_t* R, const bf16_t* Y, const float* ssqY, const float* g, float* rstd_out, float* outf, bool wf32, int row_lo, int row_hi, int yoff, int gw, int NGW, int lane) {
;     ...
;     for (int row0 = row_lo + gw; row0 < row_hi; row0 += RP * NGW) {
;         u32x4 rr[RP][2], oo[RP][2]; float ssv[RP];
; #pragma unroll
;         for (int k = 0; k < RP; ++k) { const int row = row0 + k * NGW; const bool ok = row < row_hi; const int rw = ok ? row : row0;
;             ssv[k] = ssqY[rw];
; #pragma unroll
;             for (int j = 0; j < 2; ++j) { const int c = 8 * lane + 512 * j; rr[k][j] = *(const u32x4*)(R + (size_t)rw * DM + c); oo[k][j] = *(const u32x4*)(Y + (size_t)(rw - yoff) * DM + c); } }
; #pragma unroll
;         for (int k = 0; k < RP; ++k) { const int row = row0 + k * NGW; if (row < row_hi) {
;             const float rs = __builtin_amdgcn_rsqf(ssv[k] * (1.0f / DM) + RMS_EPS); float s = 0.f;
; #pragma unroll
;             for (int j = 0; j < 2; ++j) { const int c = 8 * lane + 512 * j; const u32x4 r = rr[k][j], o = oo[k][j]; const f32x4 ga = gv[j][0], gb = gv[j][1];
;                 f32x4 ya, yb; ya[0] = bflo(r.x) + bflo(o.x) * rs * ga[0]; ya[1] = bfhi(r.x) + bfhi(o.x) * rs * ga[1]; ya[2] = bflo(r.y) + bflo(o.y) * rs * ga[2]; ya[3] = bfhi(r.y) + bfhi(o.y) * rs * ga[3];
;                 yb[0] = bflo(r.z) + bflo(o.z) * rs * gb[0]; yb[1] = bfhi(r.z) + bfhi(o.z) * rs * gb[1]; yb[2] = bflo(r.w) + bflo(o.w) * rs * gb[2]; yb[3] = bfhi(r.w) + bfhi(o.w) * rs * gb[3];
;                 if (wf32) { *(f32x4*)(outf + (size_t)row * DM + c) = ya; *(f32x4*)(outf + (size_t)row * DM + c + 4) = yb; }
;                 s += (ya[0] * ya[0] + ya[1] * ya[1]) + (ya[2] * ya[2] + ya[3] * ya[3]) + (yb[0] * yb[0] + yb[1] * yb[1]) + (yb[2] * yb[2] + yb[3] * yb[3]);
;                 u32x4 w; w.x = pk2(ya[0], ya[1]); w.y = pk2(ya[2], ya[3]); w.z = pk2(yb[0], yb[1]); w.w = pk2(yb[2], yb[3]); *(u32x4*)(R + (size_t)row * DM + c) = w; }
;             s = wave_sum(s); if (lane == 0) rstd_out[row] = __builtin_amdgcn_rsqf(s * (1.0f / DM) + RMS_EPS); } }
	v_fmamk_f32 v96, v58, 0x3a800000, v244
	v_rsq_f32_e32 v96, v96
	v_add_u32_e32 v19, 0x400000, v19
	v_add_u32_e32 v23, 0x800000, v23
	v_lshlrev_b32_e32 v106, 16, v50
	v_and_b32_e32 v107, 0xffff0000, v50
	v_lshlrev_b32_e32 v108, 16, v42
	v_and_b32_e32 v109, 0xffff0000, v42
	v_pk_mul_f32 v[106:107], v[96:97], v[106:107] op_sel_hi:[0,1]
	v_pk_fma_f32 v[98:99], v[10:11], v[106:107], v[108:109]
	v_lshlrev_b32_e32 v106, 16, v51
	v_and_b32_e32 v107, 0xffff0000, v51
	v_lshlrev_b32_e32 v108, 16, v43
	v_and_b32_e32 v109, 0xffff0000, v43
	v_pk_mul_f32 v[106:107], v[96:97], v[106:107] op_sel_hi:[0,1]
	v_pk_fma_f32 v[100:101], v[12:13], v[106:107], v[108:109]
	v_lshlrev_b32_e32 v106, 16, v52
	v_and_b32_e32 v107, 0xffff0000, v52
	v_lshlrev_b32_e32 v108, 16, v44
	v_and_b32_e32 v109, 0xffff0000, v44
	v_pk_mul_f32 v[106:107], v[96:97], v[106:107] op_sel_hi:[0,1]
	v_pk_fma_f32 v[102:103], v[14:15], v[106:107], v[108:109]
	v_lshlrev_b32_e32 v106, 16, v53
	v_and_b32_e32 v107, 0xffff0000, v53
	v_lshlrev_b32_e32 v108, 16, v45
	v_and_b32_e32 v109, 0xffff0000, v45
	v_pk_mul_f32 v[106:107], v[96:97], v[106:107] op_sel_hi:[0,1]
	v_pk_fma_f32 v[104:105], v[16:17], v[106:107], v[108:109]
	global_store_dwordx4 v23, v[98:101], s[6:7]
	global_store_dwordx4 v23, v[102:105], s[6:7] offset:16
	v_lshlrev_b32_e32 v106, 16, v54
	v_and_b32_e32 v107, 0xffff0000, v54
	v_lshlrev_b32_e32 v108, 16, v46
	v_and_b32_e32 v109, 0xffff0000, v46
	v_pk_mul_f32 v[106:107], v[96:97], v[106:107] op_sel_hi:[0,1]
	v_pk_fma_f32 v[98:99], v[2:3], v[106:107], v[108:109]
	v_lshlrev_b32_e32 v106, 16, v55
	v_and_b32_e32 v107, 0xffff0000, v55
	v_lshlrev_b32_e32 v108, 16, v47
	v_and_b32_e32 v109, 0xffff0000, v47
	v_pk_mul_f32 v[106:107], v[96:97], v[106:107] op_sel_hi:[0,1]
	v_pk_fma_f32 v[100:101], v[4:5], v[106:107], v[108:109]
	v_lshlrev_b32_e32 v106, 16, v56
	v_and_b32_e32 v107, 0xffff0000, v56
	v_lshlrev_b32_e32 v108, 16, v48
	v_and_b32_e32 v109, 0xffff0000, v48
	v_pk_mul_f32 v[106:107], v[96:97], v[106:107] op_sel_hi:[0,1]
	v_pk_fma_f32 v[102:103], v[6:7], v[106:107], v[108:109]
	v_lshlrev_b32_e32 v106, 16, v57
	v_and_b32_e32 v107, 0xffff0000, v57
	v_lshlrev_b32_e32 v108, 16, v49
	v_and_b32_e32 v109, 0xffff0000, v49
	v_pk_mul_f32 v[106:107], v[96:97], v[106:107] op_sel_hi:[0,1]
	v_pk_fma_f32 v[104:105], v[8:9], v[106:107], v[108:109]
	global_store_dwordx4 v23, v[98:101], s[6:7] offset:2048
	global_store_dwordx4 v23, v[102:105], s[6:7] offset:2064
	s_waitcnt vmcnt(17)
; __device__ __forceinline__ float bflo(unsigned w) { return __uint_as_float(w << 16); }
; __device__ __forceinline__ float bfhi(unsigned w) { return __uint_as_float(w & 0xffff0000u); }
; __device__ __forceinline__ void resid_rows(bf16_t* R, const bf16_t* Y, const float* ssqY, const float* g, float* rstd_out, float* outf, bool wf32, int row_lo, int row_hi, int yoff, int gw, int NGW, int lane) {
;     ...
;     for (int row0 = row_lo + gw; row0 < row_hi; row0 += RP * NGW) {
;         u32x4 rr[RP][2], oo[RP][2]; float ssv[RP];
; #pragma unroll
;         for (int k = 0; k < RP; ++k) { const int row = row0 + k * NGW; const bool ok = row < row_hi; const int rw = ok ? row : row0;
;             ssv[k] = ssqY[rw];
; #pragma unroll
;             for (int j = 0; j < 2; ++j) { const int c = 8 * lane + 512 * j; rr[k][j] = *(const u32x4*)(R + (size_t)rw * DM + c); oo[k][j] = *(const u32x4*)(Y + (size_t)(rw - yoff) * DM + c); } }
; #pragma unroll
;         for (int k = 0; k < RP; ++k) { const int row = row0 + k * NGW; if (row < row_hi) {
;             const float rs = __builtin_amdgcn_rsqf(ssv[k] * (1.0f / DM) + RMS_EPS); float s = 0.f;
; #pragma unroll
;             for (int j = 0; j < 2; ++j) { const int c = 8 * lane + 512 * j; const u32x4 r = rr[k][j], o = oo[k][j]; const f32x4 ga = gv[j][0], gb = gv[j][1];
;                 f32x4 ya, yb; ya[0] = bflo(r.x) + bflo(o.x) * rs * ga[0]; ya[1] = bfhi(r.x) + bfhi(o.x) * rs * ga[1]; ya[2] = bflo(r.y) + bflo(o.y) * rs * ga[2]; ya[3] = bfhi(r.y) + bfhi(o.y) * rs * ga[3];
;                 yb[0] = bflo(r.z) + bflo(o.z) * rs * gb[0]; yb[1] = bfhi(r.z) + bfhi(o.z) * rs * gb[1]; yb[2] = bflo(r.w) + bflo(o.w) * rs * gb[2]; yb[3] = bfhi(r.w) + bfhi(o.w) * rs * gb[3];
;                 if (wf32) { *(f32x4*)(outf + (size_t)row * DM + c) = ya; *(f32x4*)(outf + (size_t)row * DM + c + 4) = yb; }
;                 s += (ya[0] * ya[0] + ya[1] * ya[1]) + (ya[2] * ya[2] + ya[3] * ya[3]) + (yb[0] * yb[0] + yb[1] * yb[1]) + (yb[2] * yb[2] + yb[3] * yb[3]);
;                 u32x4 w; w.x = pk2(ya[0], ya[1]); w.y = pk2(ya[2], ya[3]); w.z = pk2(yb[0], yb[1]); w.w = pk2(yb[2], yb[3]); *(u32x4*)(R + (size_t)row * DM + c) = w; }
;             s = wave_sum(s); if (lane == 0) rstd_out[row] = __builtin_amdgcn_rsqf(s * (1.0f / DM) + RMS_EPS); } }
	v_fmamk_f32 v96, v76, 0x3a800000, v244
	v_rsq_f32_e32 v96, v96
	v_add_u32_e32 v19, 0x400000, v19
	v_add_u32_e32 v23, 0x800000, v23
	v_lshlrev_b32_e32 v106, 16, v68
	v_and_b32_e32 v107, 0xffff0000, v68
	v_lshlrev_b32_e32 v108, 16, v60
	v_and_b32_e32 v109, 0xffff0000, v60
	v_pk_mul_f32 v[106:107], v[96:97], v[106:107] op_sel_hi:[0,1]
	v_pk_fma_f32 v[98:99], v[10:11], v[106:107], v[108:109]
	v_lshlrev_b32_e32 v106, 16, v69
	v_and_b32_e32 v107, 0xffff0000, v69
	v_lshlrev_b32_e32 v108, 16, v61
	v_and_b32_e32 v109, 0xffff0000, v61
	v_pk_mul_f32 v[106:107], v[96:97], v[106:107] op_sel_hi:[0,1]
	v_pk_fma_f32 v[100:101], v[12:13], v[106:107], v[108:109]
	v_lshlrev_b32_e32 v106, 16, v70
	v_and_b32_e32 v107, 0xffff0000, v70
	v_lshlrev_b32_e32 v108, 16, v62
	v_and_b32_e32 v109, 0xffff0000, v62
	v_pk_mul_f32 v[106:107], v[96:97], v[106:107] op_sel_hi:[0,1]
	v_pk_fma_f32 v[102:103], v[14:15], v[106:107], v[108:109]
	v_lshlrev_b32_e32 v106, 16, v71
	v_and_b32_e32 v107, 0xffff0000, v71
	v_lshlrev_b32_e32 v108, 16, v63
	v_and_b32_e32 v109, 0xffff0000, v63
	v_pk_mul_f32 v[106:107], v[96:97], v[106:107] op_sel_hi:[0,1]
	v_pk_fma_f32 v[104:105], v[16:17], v[106:107], v[108:109]
	global_store_dwordx4 v23, v[98:101], s[6:7]
	global_store_dwordx4 v23, v[102:105], s[6:7] offset:16
	v_lshlrev_b32_e32 v106, 16, v72
	v_and_b32_e32 v107, 0xffff0000, v72
	v_lshlrev_b32_e32 v108, 16, v64
	v_and_b32_e32 v109, 0xffff0000, v64
	v_pk_mul_f32 v[106:107], v[96:97], v[106:107] op_sel_hi:[0,1]
	v_pk_fma_f32 v[98:99], v[2:3], v[106:107], v[108:109]
	v_lshlrev_b32_e32 v106, 16, v73
	v_and_b32_e32 v107, 0xffff0000, v73
	v_lshlrev_b32_e32 v108, 16, v65
	v_and_b32_e32 v109, 0xffff0000, v65
	v_pk_mul_f32 v[106:107], v[96:97], v[106:107] op_sel_hi:[0,1]
	v_pk_fma_f32 v[100:101], v[4:5], v[106:107], v[108:109]
	v_lshlrev_b32_e32 v106, 16, v74
	v_and_b32_e32 v107, 0xffff0000, v74
	v_lshlrev_b32_e32 v108, 16, v66
	v_and_b32_e32 v109, 0xffff0000, v66
	v_pk_mul_f32 v[106:107], v[96:97], v[106:107] op_sel_hi:[0,1]
	v_pk_fma_f32 v[102:103], v[6:7], v[106:107], v[108:109]
	v_lshlrev_b32_e32 v106, 16, v75
	v_and_b32_e32 v107, 0xffff0000, v75
	v_lshlrev_b32_e32 v108, 16, v67
	v_and_b32_e32 v109, 0xffff0000, v67
	v_pk_mul_f32 v[106:107], v[96:97], v[106:107] op_sel_hi:[0,1]
	v_pk_fma_f32 v[104:105], v[8:9], v[106:107], v[108:109]
	global_store_dwordx4 v23, v[98:101], s[6:7] offset:2048
	global_store_dwordx4 v23, v[102:105], s[6:7] offset:2064
	s_waitcnt vmcnt(12)
	v_fmamk_f32 v96, v94, 0x3a800000, v244
	v_rsq_f32_e32 v96, v96
	v_add_u32_e32 v19, 0x400000, v19
	v_add_u32_e32 v23, 0x800000, v23
	v_lshlrev_b32_e32 v106, 16, v86
	v_and_b32_e32 v107, 0xffff0000, v86
	v_lshlrev_b32_e32 v108, 16, v78
	v_and_b32_e32 v109, 0xffff0000, v78
	v_pk_mul_f32 v[106:107], v[96:97], v[106:107] op_sel_hi:[0,1]
	v_pk_fma_f32 v[98:99], v[10:11], v[106:107], v[108:109]
	v_lshlrev_b32_e32 v106, 16, v87
	v_and_b32_e32 v107, 0xffff0000, v87
	v_lshlrev_b32_e32 v108, 16, v79
	v_and_b32_e32 v109, 0xffff0000, v79
	v_pk_mul_f32 v[106:107], v[96:97], v[106:107] op_sel_hi:[0,1]
	v_pk_fma_f32 v[100:101], v[12:13], v[106:107], v[108:109]
	v_lshlrev_b32_e32 v106, 16, v88
	v_and_b32_e32 v107, 0xffff0000, v88
	v_lshlrev_b32_e32 v108, 16, v80
	v_and_b32_e32 v109, 0xffff0000, v80
	v_pk_mul_f32 v[106:107], v[96:97], v[106:107] op_sel_hi:[0,1]
	v_pk_fma_f32 v[102:103], v[14:15], v[106:107], v[108:109]
	v_lshlrev_b32_e32 v106, 16, v89
	v_and_b32_e32 v107, 0xffff0000, v89
	v_lshlrev_b32_e32 v108, 16, v81
	v_and_b32_e32 v109, 0xffff0000, v81
	v_pk_mul_f32 v[106:107], v[96:97], v[106:107] op_sel_hi:[0,1]
	v_pk_fma_f32 v[104:105], v[16:17], v[106:107], v[108:109]
	global_store_dwordx4 v23, v[98:101], s[6:7]
	global_store_dwordx4 v23, v[102:105], s[6:7] offset:16
	v_lshlrev_b32_e32 v106, 16, v90
	v_and_b32_e32 v107, 0xffff0000, v90
	v_lshlrev_b32_e32 v108, 16, v82
	v_and_b32_e32 v109, 0xffff0000, v82
	v_pk_mul_f32 v[106:107], v[96:97], v[106:107] op_sel_hi:[0,1]
	v_pk_fma_f32 v[98:99], v[2:3], v[106:107], v[108:109]
	v_lshlrev_b32_e32 v106, 16, v91
	v_and_b32_e32 v107, 0xffff0000, v91
	v_lshlrev_b32_e32 v108, 16, v83
	v_and_b32_e32 v109, 0xffff0000, v83
	v_pk_mul_f32 v[106:107], v[96:97], v[106:107] op_sel_hi:[0,1]
	v_pk_fma_f32 v[100:101], v[4:5], v[106:107], v[108:109]
	v_lshlrev_b32_e32 v106, 16, v92
	v_and_b32_e32 v107, 0xffff0000, v92
	v_lshlrev_b32_e32 v108, 16, v84
	v_and_b32_e32 v109, 0xffff0000, v84
	v_pk_mul_f32 v[106:107], v[96:97], v[106:107] op_sel_hi:[0,1]
	v_pk_fma_f32 v[102:103], v[6:7], v[106:107], v[108:109]
	v_lshlrev_b32_e32 v106, 16, v93
	v_and_b32_e32 v107, 0xffff0000, v93
	v_lshlrev_b32_e32 v108, 16, v85
	v_and_b32_e32 v109, 0xffff0000, v85
	v_pk_mul_f32 v[106:107], v[96:97], v[106:107] op_sel_hi:[0,1]
	v_pk_fma_f32 v[104:105], v[8:9], v[106:107], v[108:109]
	global_store_dwordx4 v23, v[98:101], s[6:7] offset:2048
	global_store_dwordx4 v23, v[102:105], s[6:7] offset:2064
